# differential-attention map-0 park scratch re-laid out lane-contiguous (each store/load instruction now covers 1 KB contiguous instead of 64 lines 256 B apart)
# speedup vs baseline: 1.0090x; 1.0040x over previous
;   DI float* park() const { return (float*)ws; }
; DI void diff_item(const Params& p, int b, int hh, int qt, float lam, char* smem) {
;     ...
;   attn_core<64, 1, 128>(zb + 2304 + hh * 128 + 64, LDZ1, zb + 3328 + hh * 128 + 64, LDZ1, 64, nullptr, 0, vt, qt * 256, 0, qt * 4 + 3, 0.125f * LOG2E, -1e30f, 0.f, 0, smem, O, ls);
;   const size_t tok = (size_t)b * S + qt * 256 + 32 * w + l32;
;   const float i1 = lam / ls[0];
;   float ss = 0.f;
; #pragma unroll
;   for (int db = 0; db < 4; ++db)
; #pragma unroll
;     for (int j = 0; j < 4; ++j) {
;       const f32x4 pv = park[db * 4 + j];
; #pragma unroll
;       for (int i = 0; i < 4; ++i) { const float od = pv[i] - O[0][db][4 * j + i] * i1; O[0][db][4 * j + i] = od; ss += od * od; }
.LBB0_1442:
	v_ashrrev_i32_e32 v1, 1, v140
	s_lshl_b32 s0, s6, 12
	v_and_b32_e32 v2, 0xffffffe0, v1
	s_add_i32 s6, s52, s0
	v_ashrrev_i32_e32 v3, 31, v2
	v_lshl_add_u64 v[2:3], v[2:3], 0, s[6:7]
	v_and_or_b32 v2, v140, 31, v2
	v_lshlrev_b64 v[4:5], 12, v[2:3]
	v_lshl_add_u64 v[136:137], s[22:23], 0, v[4:5]
	v_mad_u64_u32 v[4:5], s[2:3], v2, s46, v[136:137]
	v_lshrrev_b32_e32 v1, 3, v140
	s_lshl_b32 s6, s51, 1
	v_mad_i32_i24 v5, v3, s46, v5
	v_and_b32_e32 v1, 4, v1
	v_lshl_add_u64 v[2:3], v[4:5], 0, s[6:7]
	v_lshlrev_b32_e32 v138, 1, v1
	v_mov_b32_e32 v139, v0
	s_barrier
	s_mov_b32 s100, 0xffffe000
	s_mov_b32 s101, -1
	v_lshl_add_u64 v[142:143], v[142:143], 0, s[100:101]
	global_load_dwordx4 v[112:115], v[142:143], off offset:-1024
	global_load_dwordx4 v[120:123], v[142:143], off offset:-2048
	global_load_dwordx4 v[124:127], v[142:143], off offset:-3072
	global_load_dwordx4 v[128:131], v[142:143], off offset:-4096
	global_load_dwordx4 v[96:99], v[142:143], off offset:3072
	global_load_dwordx4 v[104:107], v[142:143], off offset:2048
	global_load_dwordx4 v[108:111], v[142:143], off offset:1024
	global_load_dwordx4 v[116:119], v[142:143], off
	s_mov_b32 s98, 0x2000
	s_mov_b32 s99, 0
	v_lshl_add_u64 v[142:143], v[142:143], 0, s[98:99]
	global_load_dwordx4 v[80:83], v[142:143], off offset:-1024
	global_load_dwordx4 v[88:91], v[142:143], off offset:-2048
	global_load_dwordx4 v[92:95], v[142:143], off offset:-3072
	global_load_dwordx4 v[100:103], v[142:143], off offset:-4096
	global_load_dwordx4 v[10:13], v[142:143], off offset:1024
	global_load_dwordx4 v[84:87], v[142:143], off
	global_load_dwordx4 v[6:9], v[142:143], off offset:2048
	global_load_dwordx4 v[132:135], v[142:143], off offset:3072
	v_lshl_add_u64 v[142:143], v[2:3], 0, v[138:139]
	v_add_co_u32_e32 v2, vcc, s47, v142
	s_mov_b64 s[0:1], s[24:25]
	s_nop 0
	v_addc_co_u32_e32 v3, vcc, 0, v143, vcc
	global_load_dwordx2 v[140:141], v[2:3], off offset:2560
	ds_bpermute_b32 v144, v155, v158
	v_lshl_add_u64 v[136:137], v[136:137], 0, s[6:7]
	v_lshl_add_u64 v[138:139], v[136:137], 0, v[138:139]
	v_lshl_add_u64 v[136:137], v[142:143], 0, s[30:31]
	global_load_dwordx2 v[142:143], v[136:137], off offset:240
	v_mov_b32_e32 v3, v0
	v_lshlrev_b32_e32 v2, 2, v1
	s_waitcnt lgkmcnt(0)
	v_add_f32_e32 v1, v158, v144
	v_lshl_add_u64 v[14:15], s[0:1], 0, v[2:3]
	v_div_scale_f32 v145, s[0:1], v1, v1, v152
	v_rcp_f32_e32 v144, v145
	v_div_scale_f32 v146, vcc, v152, v1, v152
	flat_load_dwordx4 v[2:5], v[14:15]
	v_fma_f32 v147, -v145, v144, 1.0
	v_fmac_f32_e32 v144, v147, v144
	v_mul_f32_e32 v147, v146, v144
	v_fma_f32 v148, -v145, v147, v146
	v_fmac_f32_e32 v147, v148, v144
	v_fma_f32 v145, -v145, v147, v146
	v_div_fmas_f32 v144, v145, v144, v147
	v_div_fixup_f32 v144, v144, v1, v152
	s_waitcnt vmcnt(0)
	v_pk_fma_f32 v[130:131], v[66:67], v[144:145], v[130:131] op_sel_hi:[1,0,1] neg_lo:[1,0,0] neg_hi:[1,0,0]
	v_pk_fma_f32 v[128:129], v[64:65], v[144:145], v[128:129] op_sel_hi:[1,0,1] neg_lo:[1,0,0] neg_hi:[1,0,0]
	v_pk_mul_f32 v[148:149], v[130:131], v[130:131]
	v_pk_mul_f32 v[150:151], v[128:129], v[128:129]
	v_pk_fma_f32 v[132:133], v[28:29], v[144:145], v[132:133] op_sel_hi:[1,0,1] neg_lo:[1,0,0] neg_hi:[1,0,0]
	v_pk_fma_f32 v[28:29], v[30:31], v[144:145], v[134:135] op_sel_hi:[1,0,1] neg_lo:[1,0,0] neg_hi:[1,0,0]
	v_pk_mul_f32 v[134:135], v[132:133], v[132:133]
	v_pk_mul_f32 v[146:147], v[28:29], v[28:29]
	v_lshlrev_b32_e32 v1, 16, v140
	v_and_b32_e32 v66, 0xffff0000, v140
	v_mul_f32_e32 v30, 0xbfb8aa3b, v1
	v_mul_f32_e32 v31, 0xbfb8aa3b, v66
	v_exp_f32_e32 v30, v30
	v_exp_f32_e32 v31, v31
	v_lshlrev_b32_e32 v168, 16, v141
	v_and_b32_e32 v67, 0xffff0000, v141
	v_mul_f32_e32 v64, 0xbfb8aa3b, v168
	v_pk_add_f32 v[30:31], v[30:31], 1.0 op_sel_hi:[1,0]
	v_mul_f32_e32 v65, 0xbfb8aa3b, v67
	v_div_scale_f32 v140, s[0:1], v31, v31, v66
	v_rcp_f32_e32 v156, v140
	v_div_scale_f32 v145, s[0:1], v30, v30, v1
	v_rcp_f32_e32 v158, v145
	v_fma_f32 v159, -v140, v156, 1.0
	v_div_scale_f32 v141, vcc, v66, v31, v66
	v_fmac_f32_e32 v156, v159, v156
	v_mul_f32_e32 v159, v141, v156
	v_fma_f32 v161, -v140, v159, v141
	v_fma_f32 v160, -v145, v158, 1.0
	v_fmac_f32_e32 v159, v161, v156
	v_exp_f32_e32 v64, v64
	v_exp_f32_e32 v65, v65
	v_div_scale_f32 v157, s[0:1], v1, v30, v1
	v_fmac_f32_e32 v158, v160, v158
	v_fma_f32 v140, -v140, v159, v141
	v_mul_f32_e32 v160, v157, v158
	v_div_fmas_f32 v140, v140, v156, v159
	v_div_fixup_f32 v141, v140, v31, v66
	v_fma_f32 v31, -v145, v160, v157
	v_fmac_f32_e32 v160, v31, v158
	v_fma_f32 v31, -v145, v160, v157
	v_pk_add_f32 v[156:157], v[64:65], 1.0 op_sel_hi:[1,0]
	s_mov_b64 vcc, s[0:1]
	v_div_scale_f32 v64, s[2:3], v157, v157, v67
	v_rcp_f32_e32 v65, v64
	v_div_fmas_f32 v31, v31, v158, v160
	v_div_fixup_f32 v140, v31, v30, v1
	global_load_dwordx2 v[158:159], v[136:137], off offset:16
	v_fma_f32 v1, -v64, v65, 1.0
	v_fmac_f32_e32 v65, v1, v65
	v_div_scale_f32 v1, vcc, v67, v157, v67
	v_mul_f32_e32 v30, v1, v65
	v_fma_f32 v31, -v64, v30, v1
	v_fmac_f32_e32 v30, v31, v65
	v_fma_f32 v1, -v64, v30, v1
	v_div_fmas_f32 v1, v1, v65, v30
	v_div_fixup_f32 v145, v1, v157, v67
	v_pk_fma_f32 v[30:31], v[16:17], v[144:145], v[84:85] op_sel_hi:[1,0,1] neg_lo:[1,0,0] neg_hi:[1,0,0]
	v_pk_fma_f32 v[16:17], v[20:21], v[144:145], v[10:11] op_sel_hi:[1,0,1] neg_lo:[1,0,0] neg_hi:[1,0,0]
	v_pk_fma_f32 v[10:11], v[24:25], v[144:145], v[6:7] op_sel_hi:[1,0,1] neg_lo:[1,0,0] neg_hi:[1,0,0]
	v_add_f32_e32 v24, v150, v151
	v_pk_fma_f32 v[124:125], v[68:69], v[144:145], v[124:125] op_sel_hi:[1,0,1] neg_lo:[1,0,0] neg_hi:[1,0,0]
	v_add_f32_e32 v24, v148, v24
	v_pk_mul_f32 v[162:163], v[124:125], v[124:125]
;   DI float* park() const { return (float*)ws; }
; DI void diff_item(const Params& p, int b, int hh, int qt, float lam, char* smem) {
;     ...
;   float ss = 0.f;
; #pragma unroll
;   for (int db = 0; db < 4; ++db)
; #pragma unroll
;     for (int j = 0; j < 4; ++j) {
;       const f32x4 pv = park[db * 4 + j];
; #pragma unroll
;       for (int i = 0; i < 4; ++i) { const float od = pv[i] - O[0][db][4 * j + i] * i1; O[0][db][4 * j + i] = od; ss += od * od; }
;     }
;   ss += __shfl_xor(ss, 32);
	v_add_f32_e32 v24, v149, v24
	v_pk_fma_f32 v[126:127], v[70:71], v[144:145], v[126:127] op_sel_hi:[1,0,1] neg_lo:[1,0,0] neg_hi:[1,0,0]
	v_add_f32_e32 v24, v162, v24
	v_pk_mul_f32 v[160:161], v[126:127], v[126:127]
	v_add_f32_e32 v24, v163, v24
	v_pk_fma_f32 v[120:121], v[72:73], v[144:145], v[120:121] op_sel_hi:[1,0,1] neg_lo:[1,0,0] neg_hi:[1,0,0]
	v_add_f32_e32 v24, v160, v24
	v_pk_mul_f32 v[166:167], v[120:121], v[120:121]
	v_add_f32_e32 v24, v161, v24
	v_pk_fma_f32 v[122:123], v[74:75], v[144:145], v[122:123] op_sel_hi:[1,0,1] neg_lo:[1,0,0] neg_hi:[1,0,0]
	v_add_f32_e32 v24, v166, v24
	v_pk_mul_f32 v[164:165], v[122:123], v[122:123]
	v_add_f32_e32 v24, v167, v24
	v_pk_fma_f32 v[76:77], v[76:77], v[144:145], v[112:113] op_sel_hi:[1,0,1] neg_lo:[1,0,0] neg_hi:[1,0,0]
	v_add_f32_e32 v24, v164, v24
	v_pk_mul_f32 v[112:113], v[76:77], v[76:77]
	v_add_f32_e32 v24, v165, v24
	v_pk_fma_f32 v[78:79], v[78:79], v[144:145], v[114:115] op_sel_hi:[1,0,1] neg_lo:[1,0,0] neg_hi:[1,0,0]
	v_add_f32_e32 v24, v112, v24
	v_pk_mul_f32 v[114:115], v[78:79], v[78:79]
	v_add_f32_e32 v24, v113, v24
	v_pk_fma_f32 v[74:75], v[48:49], v[144:145], v[116:117] op_sel_hi:[1,0,1] neg_lo:[1,0,0] neg_hi:[1,0,0]
	v_add_f32_e32 v24, v114, v24
	v_pk_mul_f32 v[116:117], v[74:75], v[74:75]
	v_add_f32_e32 v24, v115, v24
	v_pk_fma_f32 v[72:73], v[50:51], v[144:145], v[118:119] op_sel_hi:[1,0,1] neg_lo:[1,0,0] neg_hi:[1,0,0]
	v_add_f32_e32 v24, v116, v24
	v_pk_mul_f32 v[118:119], v[72:73], v[72:73]
	v_add_f32_e32 v24, v117, v24
	v_pk_fma_f32 v[70:71], v[52:53], v[144:145], v[108:109] op_sel_hi:[1,0,1] neg_lo:[1,0,0] neg_hi:[1,0,0]
	v_add_f32_e32 v24, v118, v24
	v_pk_mul_f32 v[108:109], v[70:71], v[70:71]
	v_add_f32_e32 v24, v119, v24
	v_pk_fma_f32 v[68:69], v[54:55], v[144:145], v[110:111] op_sel_hi:[1,0,1] neg_lo:[1,0,0] neg_hi:[1,0,0]
	v_add_f32_e32 v24, v108, v24
	v_pk_mul_f32 v[110:111], v[68:69], v[68:69]
	v_add_f32_e32 v24, v109, v24
	v_pk_fma_f32 v[66:67], v[56:57], v[144:145], v[104:105] op_sel_hi:[1,0,1] neg_lo:[1,0,0] neg_hi:[1,0,0]
	v_add_f32_e32 v24, v110, v24
	v_pk_mul_f32 v[104:105], v[66:67], v[66:67]
	v_add_f32_e32 v24, v111, v24
	v_pk_fma_f32 v[64:65], v[58:59], v[144:145], v[106:107] op_sel_hi:[1,0,1] neg_lo:[1,0,0] neg_hi:[1,0,0]
	v_add_f32_e32 v24, v104, v24
	v_pk_mul_f32 v[106:107], v[64:65], v[64:65]
	v_add_f32_e32 v24, v105, v24
	v_pk_fma_f32 v[58:59], v[60:61], v[144:145], v[96:97] op_sel_hi:[1,0,1] neg_lo:[1,0,0] neg_hi:[1,0,0]
	v_add_f32_e32 v24, v106, v24
	v_pk_mul_f32 v[60:61], v[58:59], v[58:59]
	v_add_f32_e32 v24, v107, v24
	v_pk_fma_f32 v[56:57], v[62:63], v[144:145], v[98:99] op_sel_hi:[1,0,1] neg_lo:[1,0,0] neg_hi:[1,0,0]
	v_add_f32_e32 v24, v60, v24
	v_pk_mul_f32 v[62:63], v[56:57], v[56:57]
	v_add_f32_e32 v24, v61, v24
	v_pk_fma_f32 v[54:55], v[32:33], v[144:145], v[100:101] op_sel_hi:[1,0,1] neg_lo:[1,0,0] neg_hi:[1,0,0]
	v_add_f32_e32 v24, v62, v24
	v_pk_mul_f32 v[98:99], v[54:55], v[54:55]
	v_add_f32_e32 v24, v63, v24
	v_pk_fma_f32 v[52:53], v[34:35], v[144:145], v[102:103] op_sel_hi:[1,0,1] neg_lo:[1,0,0] neg_hi:[1,0,0]
	v_add_f32_e32 v24, v98, v24
	v_pk_mul_f32 v[96:97], v[52:53], v[52:53]
	v_add_f32_e32 v24, v99, v24
	v_pk_fma_f32 v[50:51], v[36:37], v[144:145], v[92:93] op_sel_hi:[1,0,1] neg_lo:[1,0,0] neg_hi:[1,0,0]
	v_add_f32_e32 v24, v96, v24
	v_pk_mul_f32 v[92:93], v[50:51], v[50:51]
	v_add_f32_e32 v24, v97, v24
	v_pk_fma_f32 v[48:49], v[38:39], v[144:145], v[94:95] op_sel_hi:[1,0,1] neg_lo:[1,0,0] neg_hi:[1,0,0]
	v_add_f32_e32 v24, v92, v24
	v_pk_mul_f32 v[94:95], v[48:49], v[48:49]
	v_add_f32_e32 v24, v93, v24
	v_pk_fma_f32 v[38:39], v[40:41], v[144:145], v[88:89] op_sel_hi:[1,0,1] neg_lo:[1,0,0] neg_hi:[1,0,0]
	v_add_f32_e32 v24, v94, v24
	v_pk_mul_f32 v[40:41], v[38:39], v[38:39]
	v_add_f32_e32 v24, v95, v24
	v_pk_fma_f32 v[36:37], v[42:43], v[144:145], v[90:91] op_sel_hi:[1,0,1] neg_lo:[1,0,0] neg_hi:[1,0,0]
	v_add_f32_e32 v24, v40, v24
	v_pk_mul_f32 v[42:43], v[36:37], v[36:37]
	v_add_f32_e32 v24, v41, v24
	v_pk_fma_f32 v[34:35], v[44:45], v[144:145], v[80:81] op_sel_hi:[1,0,1] neg_lo:[1,0,0] neg_hi:[1,0,0]
	v_add_f32_e32 v24, v42, v24
	v_pk_mul_f32 v[44:45], v[34:35], v[34:35]
	v_add_f32_e32 v24, v43, v24
	v_pk_fma_f32 v[32:33], v[46:47], v[144:145], v[82:83] op_sel_hi:[1,0,1] neg_lo:[1,0,0] neg_hi:[1,0,0]
	v_add_f32_e32 v24, v44, v24
	v_pk_mul_f32 v[46:47], v[32:33], v[32:33]
	v_add_f32_e32 v24, v45, v24
	v_add_f32_e32 v24, v46, v24
	v_pk_mul_f32 v[82:83], v[30:31], v[30:31]
	v_add_f32_e32 v24, v47, v24
	v_pk_fma_f32 v[18:19], v[18:19], v[144:145], v[86:87] op_sel_hi:[1,0,1] neg_lo:[1,0,0] neg_hi:[1,0,0]
	v_add_f32_e32 v24, v82, v24
	v_pk_mul_f32 v[80:81], v[18:19], v[18:19]
	v_add_f32_e32 v24, v83, v24
	v_add_f32_e32 v24, v80, v24
	v_pk_mul_f32 v[20:21], v[16:17], v[16:17]
	v_add_f32_e32 v24, v81, v24
	v_pk_fma_f32 v[12:13], v[22:23], v[144:145], v[12:13] op_sel_hi:[1,0,1] neg_lo:[1,0,0] neg_hi:[1,0,0]
	v_add_f32_e32 v20, v20, v24
	v_pk_mul_f32 v[22:23], v[12:13], v[12:13]
	v_add_f32_e32 v20, v21, v20
	v_add_f32_e32 v20, v22, v20
	v_pk_mul_f32 v[6:7], v[10:11], v[10:11]
	v_add_f32_e32 v20, v23, v20
	v_pk_fma_f32 v[8:9], v[26:27], v[144:145], v[8:9] op_sel_hi:[1,0,1] neg_lo:[1,0,0] neg_hi:[1,0,0]
	v_add_f32_e32 v6, v6, v20
	v_pk_mul_f32 v[26:27], v[8:9], v[8:9]
	v_add_f32_e32 v6, v7, v6
	v_add_f32_e32 v6, v26, v6
	v_add_f32_e32 v6, v27, v6
	v_add_f32_e32 v6, v134, v6
	v_add_f32_e32 v6, v135, v6
	v_add_f32_e32 v6, v146, v6
	v_add_f32_e32 v6, v147, v6
	ds_bpermute_b32 v7, v155, v6
	v_div_scale_f32 v169, s[0:1], v156, v156, v168
	v_rcp_f32_e32 v170, v169
	s_waitcnt vmcnt(0)
	v_lshlrev_b32_e32 v47, 16, v159
	s_waitcnt lgkmcnt(0)
;   DI bf16_t* h() const { return (bf16_t*)(ws + OFF_H); }
;   DI bf16_t* z() const { return (bf16_t*)(ws + OFF_Z); }
; DI float bflo(unsigned u) { return __uint_as_float(u << 16); }
; DI float bfhi(unsigned u) { return __uint_as_float(u & 0xffff0000u); }
; DI float siluf_(float v) { return v / (1.f + __expf(-v)); }
; DI void store_bf4(bf16_t* dst, float a, float b, float c, float d) { u32x2 w; w.x = pk_bf16(a, b); w.y = pk_bf16(c, d); *(u32x2*)dst = w; }
; DI void diff_item(const Params& p, int b, int hh, int qt, float lam, char* smem) {
;     ...
;   ss += __shfl_xor(ss, 32);
;   const float rstd = rsqrtf(ss * (1.f / 128.f) + EPS) * (1.f - LAMBDA_INIT);
;   const float* slp = p.subln; asm volatile("" : "+s"(slp));
;   bf16_t* yrow = p.h() + tok * D + 1024 + hh * 128;
;   const bf16_t* grow = p.z() + tok * LDZ1 + 5376 + hh * 128;
; #pragma unroll
;   for (int db = 0; db < 4; ++db)
; #pragma unroll
;     for (int j = 0; j < 4; ++j) {
;       const int dv = 32 * db + 8 * j + 4 * g;
;       const u32x2 gr = *(const u32x2*)(grow + dv);
;       const f32x4 sl = *(const f32x4*)(slp + dv);
;       store_bf4(yrow + dv, O[0][db][4 * j] * rstd * sl[0] * siluf_(bflo(gr.x)), O[0][db][4 * j + 1] * rstd * sl[1] * siluf_(bfhi(gr.x)),
;                 O[0][db][4 * j + 2] * rstd * sl[2] * siluf_(bflo(gr.y)), O[0][db][4 * j + 3] * rstd * sl[3] * siluf_(bfhi(gr.y)));
	v_add_f32_e32 v6, v6, v7
	v_fmamk_f32 v6, v6, 0x3c000000, v153
	v_fma_f32 v1, -v169, v170, 1.0
	v_fmac_f32_e32 v170, v1, v170
	v_div_scale_f32 v1, vcc, v168, v156, v168
	v_mul_f32_e32 v7, 0x4b800000, v6
	v_cmp_gt_f32_e64 s[0:1], s48, v6
	v_mul_f32_e32 v20, v1, v170
	v_fma_f32 v21, -v169, v20, v1
	v_cndmask_b32_e64 v6, v6, v7, s[0:1]
	v_rsq_f32_e32 v6, v6
	v_fmac_f32_e32 v20, v21, v170
	v_fma_f32 v1, -v169, v20, v1
	v_div_fmas_f32 v1, v1, v170, v20
	v_div_fixup_f32 v144, v1, v156, v168
	v_mul_f32_e32 v1, 0x45800000, v6
	v_cndmask_b32_e64 v1, v6, v1, s[0:1]
	v_mul_f32_e32 v6, 0x3f24fd5c, v1
	v_pk_mul_f32 v[20:21], v[128:129], v[6:7] op_sel_hi:[1,0]
	v_lshlrev_b32_e32 v1, 16, v158
	v_pk_mul_f32 v[2:3], v[2:3], v[20:21]
	v_pk_mul_f32 v[20:21], v[130:131], v[6:7] op_sel_hi:[1,0]
	v_pk_mul_f32 v[2:3], v[140:141], v[2:3]
	v_pk_mul_f32 v[4:5], v[4:5], v[20:21]
	v_cvt_pk_bf16_f32 v2, v2, v3
	v_pk_mul_f32 v[4:5], v[144:145], v[4:5]
	v_and_b32_e32 v7, 0xffff0000, v158
	v_cvt_pk_bf16_f32 v3, v4, v5
	v_add_co_u32_e32 v4, vcc, s49, v138
	v_and_b32_e32 v60, 0xffff0000, v159
	s_nop 0
	v_addc_co_u32_e32 v5, vcc, 0, v139, vcc
	global_store_dwordx2 v[4:5], v[2:3], off offset:2048
	flat_load_dwordx4 v[20:23], v[14:15] offset:32
	s_nop 0
	global_load_dwordx2 v[4:5], v[136:137], off offset:32
	global_load_dwordx2 v[24:25], v[136:137], off offset:48
	global_load_dwordx2 v[26:27], v[136:137], off offset:64
	v_mul_f32_e32 v2, 0xbfb8aa3b, v1
	v_mul_f32_e32 v3, 0xbfb8aa3b, v7
	v_exp_f32_e32 v2, v2
	v_exp_f32_e32 v3, v3
	s_nop 0
	v_pk_add_f32 v[40:41], v[2:3], 1.0 op_sel_hi:[1,0]
	s_nop 0
	v_div_scale_f32 v42, s[0:1], v41, v41, v7
	v_rcp_f32_e32 v43, v42
	v_lshl_add_u64 v[2:3], v[138:139], 0, s[34:35]
	v_fma_f32 v44, -v42, v43, 1.0
	v_fmac_f32_e32 v43, v44, v43
	v_div_scale_f32 v44, vcc, v7, v41, v7
	v_mul_f32_e32 v45, v44, v43
	v_fma_f32 v46, -v42, v45, v44
	v_fmac_f32_e32 v45, v46, v43
	v_fma_f32 v42, -v42, v45, v44
	v_div_scale_f32 v44, s[0:1], v40, v40, v1
	v_rcp_f32_e32 v46, v44
	v_div_fmas_f32 v42, v42, v43, v45
	v_div_fixup_f32 v41, v42, v41, v7
	v_mul_f32_e32 v42, 0xbfb8aa3b, v47
	v_mul_f32_e32 v43, 0xbfb8aa3b, v60
	v_fma_f32 v7, -v44, v46, 1.0
	v_exp_f32_e32 v42, v42
	v_exp_f32_e32 v43, v43
	v_fmac_f32_e32 v46, v7, v46
	v_div_scale_f32 v7, vcc, v1, v40, v1
	v_mul_f32_e32 v45, v7, v46
	v_fma_f32 v61, -v44, v45, v7
	v_fmac_f32_e32 v45, v61, v46
	v_pk_add_f32 v[42:43], v[42:43], 1.0 op_sel_hi:[1,0]
	v_fma_f32 v7, -v44, v45, v7
	v_div_scale_f32 v44, s[0:1], v43, v43, v60
	v_rcp_f32_e32 v61, v44
	v_div_fmas_f32 v7, v7, v46, v45
	v_div_fixup_f32 v40, v7, v40, v1
	v_fma_f32 v1, -v44, v61, 1.0
	v_fmac_f32_e32 v61, v1, v61
	v_div_scale_f32 v1, vcc, v60, v43, v60
	v_mul_f32_e32 v7, v1, v61
	v_fma_f32 v45, -v44, v7, v1
	v_fmac_f32_e32 v7, v45, v61
	v_fma_f32 v1, -v44, v7, v1
	v_div_scale_f32 v44, s[0:1], v42, v42, v47
	v_rcp_f32_e32 v45, v44
	v_div_fmas_f32 v1, v1, v61, v7
	v_div_fixup_f32 v43, v1, v43, v60
	v_fma_f32 v1, -v44, v45, 1.0
	v_fmac_f32_e32 v45, v1, v45
	v_div_scale_f32 v1, vcc, v47, v42, v47
	v_mul_f32_e32 v7, v1, v45
	v_fma_f32 v46, -v44, v7, v1
	v_fmac_f32_e32 v7, v46, v45
	v_fma_f32 v1, -v44, v7, v1
	v_div_fmas_f32 v1, v1, v45, v7
	v_pk_mul_f32 v[44:45], v[124:125], v[6:7] op_sel_hi:[1,0]
	v_div_fixup_f32 v42, v1, v42, v47
	s_waitcnt vmcnt(0) lgkmcnt(0)
	v_pk_mul_f32 v[20:21], v[20:21], v[44:45]
	s_nop 0
	v_pk_mul_f32 v[20:21], v[40:41], v[20:21]
	v_pk_mul_f32 v[40:41], v[126:127], v[6:7] op_sel_hi:[1,0]
	v_cvt_pk_bf16_f32 v20, v20, v21
	v_pk_mul_f32 v[22:23], v[22:23], v[40:41]
	v_lshlrev_b32_e32 v1, 16, v4
	v_pk_mul_f32 v[22:23], v[42:43], v[22:23]
	v_and_b32_e32 v4, 0xffff0000, v4
	v_cvt_pk_bf16_f32 v21, v22, v23
	global_store_dwordx2 v[2:3], v[20:21], off offset:16
	flat_load_dwordx4 v[20:23], v[14:15] offset:64
	v_mul_f32_e32 v7, 0xbfb8aa3b, v1
	v_exp_f32_e32 v40, v7
	v_mul_f32_e32 v7, 0xbfb8aa3b, v4
	v_exp_f32_e32 v41, v7
	v_and_b32_e32 v46, 0xffff0000, v5
	v_pk_add_f32 v[40:41], v[40:41], 1.0 op_sel_hi:[1,0]
	s_nop 0
	v_div_scale_f32 v7, s[0:1], v41, v41, v4
	v_rcp_f32_e32 v42, v7
	s_nop 0
	v_fma_f32 v43, -v7, v42, 1.0
	v_fmac_f32_e32 v42, v43, v42
	v_div_scale_f32 v43, vcc, v4, v41, v4
	v_mul_f32_e32 v44, v43, v42
	v_fma_f32 v45, -v7, v44, v43
	v_fmac_f32_e32 v44, v45, v42
	v_fma_f32 v7, -v7, v44, v43
	v_div_scale_f32 v43, s[0:1], v40, v40, v1
	v_rcp_f32_e32 v45, v43
	v_div_fmas_f32 v7, v7, v42, v44
	v_div_fixup_f32 v41, v7, v41, v4
	v_lshlrev_b32_e32 v44, 16, v5
	v_fma_f32 v4, -v43, v45, 1.0
	v_fmac_f32_e32 v45, v4, v45
	v_mul_f32_e32 v4, 0xbfb8aa3b, v44
	v_mul_f32_e32 v5, 0xbfb8aa3b, v46
	v_exp_f32_e32 v4, v4
	v_exp_f32_e32 v5, v5
	v_div_scale_f32 v7, vcc, v1, v40, v1
	v_mul_f32_e32 v42, v7, v45
	v_fma_f32 v47, -v43, v42, v7
	v_fmac_f32_e32 v42, v47, v45
	v_pk_add_f32 v[4:5], v[4:5], 1.0 op_sel_hi:[1,0]
	v_fma_f32 v7, -v43, v42, v7
	v_div_scale_f32 v43, s[0:1], v5, v5, v46
	v_rcp_f32_e32 v47, v43
	v_div_fmas_f32 v7, v7, v45, v42
	v_div_fixup_f32 v40, v7, v40, v1
	v_fma_f32 v1, -v43, v47, 1.0
	v_fmac_f32_e32 v47, v1, v47
	v_div_scale_f32 v1, vcc, v46, v5, v46
	v_mul_f32_e32 v7, v1, v47
	v_fma_f32 v42, -v43, v7, v1
	v_fmac_f32_e32 v7, v42, v47
	v_div_scale_f32 v42, s[0:1], v4, v4, v44
	v_fma_f32 v1, -v43, v7, v1
	v_rcp_f32_e32 v43, v42
	v_div_fmas_f32 v1, v1, v47, v7
	v_div_fixup_f32 v5, v1, v5, v46
	v_fma_f32 v1, -v42, v43, 1.0
	v_fmac_f32_e32 v43, v1, v43
	v_div_scale_f32 v1, vcc, v44, v4, v44
	v_mul_f32_e32 v7, v1, v43
	v_fma_f32 v45, -v42, v7, v1
	v_fmac_f32_e32 v7, v45, v43
	v_fma_f32 v1, -v42, v7, v1
	v_div_fmas_f32 v1, v1, v43, v7
	v_pk_mul_f32 v[42:43], v[120:121], v[6:7] op_sel_hi:[1,0]
	v_div_fixup_f32 v4, v1, v4, v44
	v_lshlrev_b32_e32 v1, 16, v24
	v_and_b32_e32 v44, 0xffff0000, v25
	s_waitcnt vmcnt(0) lgkmcnt(0)
; DI float bflo(unsigned u) { return __uint_as_float(u << 16); }
; DI float bfhi(unsigned u) { return __uint_as_float(u & 0xffff0000u); }
; DI float siluf_(float v) { return v / (1.f + __expf(-v)); }
; DI void store_bf4(bf16_t* dst, float a, float b, float c, float d) { u32x2 w; w.x = pk_bf16(a, b); w.y = pk_bf16(c, d); *(u32x2*)dst = w; }
; DI void diff_item(const Params& p, int b, int hh, int qt, float lam, char* smem) {
;     ...
; #pragma unroll
;   for (int db = 0; db < 4; ++db)
; #pragma unroll
;     for (int j = 0; j < 4; ++j) {
;       const int dv = 32 * db + 8 * j + 4 * g;
;       const u32x2 gr = *(const u32x2*)(grow + dv);
;       const f32x4 sl = *(const f32x4*)(slp + dv);
;       store_bf4(yrow + dv, O[0][db][4 * j] * rstd * sl[0] * siluf_(bflo(gr.x)), O[0][db][4 * j + 1] * rstd * sl[1] * siluf_(bfhi(gr.x)),
;                 O[0][db][4 * j + 2] * rstd * sl[2] * siluf_(bflo(gr.y)), O[0][db][4 * j + 3] * rstd * sl[3] * siluf_(bfhi(gr.y)));
	v_pk_mul_f32 v[20:21], v[20:21], v[42:43]
	s_nop 0
	v_pk_mul_f32 v[20:21], v[40:41], v[20:21]
	v_pk_mul_f32 v[40:41], v[122:123], v[6:7] op_sel_hi:[1,0]
	v_cvt_pk_bf16_f32 v20, v20, v21
	v_pk_mul_f32 v[22:23], v[22:23], v[40:41]
	v_and_b32_e32 v7, 0xffff0000, v24
	v_pk_mul_f32 v[4:5], v[4:5], v[22:23]
	s_nop 0
	v_cvt_pk_bf16_f32 v21, v4, v5
	global_store_dwordx2 v[2:3], v[20:21], off offset:32
	flat_load_dwordx4 v[20:23], v[14:15] offset:96
	v_mul_f32_e32 v4, 0xbfb8aa3b, v1
	v_mul_f32_e32 v5, 0xbfb8aa3b, v7
	v_exp_f32_e32 v4, v4
	v_exp_f32_e32 v5, v5
	s_nop 0
	v_pk_add_f32 v[4:5], v[4:5], 1.0 op_sel_hi:[1,0]
	s_nop 0
	v_div_scale_f32 v24, s[0:1], v5, v5, v7
	v_rcp_f32_e32 v40, v24
	s_nop 0
	v_fma_f32 v41, -v24, v40, 1.0
	v_fmac_f32_e32 v40, v41, v40
	v_div_scale_f32 v41, vcc, v7, v5, v7
	v_mul_f32_e32 v42, v41, v40
	v_fma_f32 v43, -v24, v42, v41
	v_fmac_f32_e32 v42, v43, v40
	v_fma_f32 v24, -v24, v42, v41
	v_div_scale_f32 v41, s[0:1], v4, v4, v1
	v_rcp_f32_e32 v43, v41
	v_div_fmas_f32 v24, v24, v40, v42
	v_lshlrev_b32_e32 v42, 16, v25
	v_div_fixup_f32 v5, v24, v5, v7
	v_mul_f32_e32 v24, 0xbfb8aa3b, v42
	v_mul_f32_e32 v25, 0xbfb8aa3b, v44
	v_fma_f32 v7, -v41, v43, 1.0
	v_exp_f32_e32 v24, v24
	v_exp_f32_e32 v25, v25
	v_fmac_f32_e32 v43, v7, v43
	v_div_scale_f32 v7, vcc, v1, v4, v1
	v_mul_f32_e32 v40, v7, v43
	v_fma_f32 v45, -v41, v40, v7
	v_fmac_f32_e32 v40, v45, v43
	v_pk_add_f32 v[24:25], v[24:25], 1.0 op_sel_hi:[1,0]
	v_fma_f32 v7, -v41, v40, v7
	v_div_scale_f32 v41, s[0:1], v25, v25, v44
	v_rcp_f32_e32 v45, v41
	v_div_fmas_f32 v7, v7, v43, v40
	v_div_fixup_f32 v4, v7, v4, v1
	v_fma_f32 v1, -v41, v45, 1.0
	v_fmac_f32_e32 v45, v1, v45
	v_div_scale_f32 v1, vcc, v44, v25, v44
	v_mul_f32_e32 v7, v1, v45
	v_fma_f32 v40, -v41, v7, v1
	v_fmac_f32_e32 v7, v40, v45
	v_div_scale_f32 v40, s[0:1], v24, v24, v42
	v_fma_f32 v1, -v41, v7, v1
	v_rcp_f32_e32 v41, v40
	v_div_fmas_f32 v1, v1, v45, v7
	v_div_fixup_f32 v25, v1, v25, v44
	v_and_b32_e32 v44, 0xffff0000, v27
	v_fma_f32 v1, -v40, v41, 1.0
	v_fmac_f32_e32 v41, v1, v41
	v_div_scale_f32 v1, vcc, v42, v24, v42
	v_mul_f32_e32 v7, v1, v41
	v_fma_f32 v43, -v40, v7, v1
	v_fmac_f32_e32 v7, v43, v41
	v_fma_f32 v1, -v40, v7, v1
	v_div_fmas_f32 v1, v1, v41, v7
	v_pk_mul_f32 v[40:41], v[76:77], v[6:7] op_sel_hi:[1,0]
	v_div_fixup_f32 v24, v1, v24, v42
	v_lshlrev_b32_e32 v1, 16, v26
	s_waitcnt vmcnt(0) lgkmcnt(0)
	v_pk_mul_f32 v[20:21], v[20:21], v[40:41]
	s_nop 0
	v_pk_mul_f32 v[4:5], v[4:5], v[20:21]
	v_pk_mul_f32 v[20:21], v[78:79], v[6:7] op_sel_hi:[1,0]
	v_cvt_pk_bf16_f32 v4, v4, v5
	v_pk_mul_f32 v[20:21], v[22:23], v[20:21]
	v_and_b32_e32 v7, 0xffff0000, v26
	v_pk_mul_f32 v[20:21], v[24:25], v[20:21]
	global_load_dwordx2 v[24:25], v[136:137], off offset:80
	v_cvt_pk_bf16_f32 v5, v20, v21
	global_store_dwordx2 v[2:3], v[4:5], off offset:48
	flat_load_dwordx4 v[20:23], v[14:15] offset:128
	v_mul_f32_e32 v4, 0xbfb8aa3b, v1
	v_mul_f32_e32 v5, 0xbfb8aa3b, v7
	v_exp_f32_e32 v4, v4
	v_exp_f32_e32 v5, v5
	s_waitcnt vmcnt(0)
	v_and_b32_e32 v60, 0xffff0000, v25
	v_pk_add_f32 v[4:5], v[4:5], 1.0 op_sel_hi:[1,0]
	s_nop 0
	v_div_scale_f32 v26, s[0:1], v5, v5, v7
	v_rcp_f32_e32 v40, v26
	s_nop 0
	v_fma_f32 v41, -v26, v40, 1.0
	v_fmac_f32_e32 v40, v41, v40
	v_div_scale_f32 v41, vcc, v7, v5, v7
	v_mul_f32_e32 v42, v41, v40
	v_fma_f32 v43, -v26, v42, v41
	v_fmac_f32_e32 v42, v43, v40
	v_fma_f32 v26, -v26, v42, v41
	v_div_scale_f32 v41, s[0:1], v4, v4, v1
	v_rcp_f32_e32 v43, v41
	v_div_fmas_f32 v26, v26, v40, v42
	v_lshlrev_b32_e32 v42, 16, v27
	v_div_fixup_f32 v5, v26, v5, v7
	v_mul_f32_e32 v26, 0xbfb8aa3b, v42
	v_mul_f32_e32 v27, 0xbfb8aa3b, v44
	v_fma_f32 v7, -v41, v43, 1.0
	v_exp_f32_e32 v26, v26
	v_exp_f32_e32 v27, v27
	v_fmac_f32_e32 v43, v7, v43
	v_div_scale_f32 v7, vcc, v1, v4, v1
	v_mul_f32_e32 v40, v7, v43
	v_fma_f32 v45, -v41, v40, v7
	v_fmac_f32_e32 v40, v45, v43
	v_pk_add_f32 v[26:27], v[26:27], 1.0 op_sel_hi:[1,0]
	v_fma_f32 v7, -v41, v40, v7
	v_div_scale_f32 v41, s[0:1], v27, v27, v44
	v_rcp_f32_e32 v45, v41
	v_div_fmas_f32 v7, v7, v43, v40
	v_div_fixup_f32 v4, v7, v4, v1
	v_fma_f32 v1, -v41, v45, 1.0
	v_fmac_f32_e32 v45, v1, v45
	v_div_scale_f32 v1, vcc, v44, v27, v44
	v_mul_f32_e32 v7, v1, v45
	v_fma_f32 v40, -v41, v7, v1
	v_fmac_f32_e32 v7, v40, v45
	v_div_scale_f32 v40, s[0:1], v26, v26, v42
	v_fma_f32 v1, -v41, v7, v1
	v_rcp_f32_e32 v41, v40
	v_div_fmas_f32 v1, v1, v45, v7
	v_div_fixup_f32 v27, v1, v27, v44
	v_fma_f32 v1, -v40, v41, 1.0
	v_fmac_f32_e32 v41, v1, v41
	v_div_scale_f32 v1, vcc, v42, v26, v42
	v_mul_f32_e32 v7, v1, v41
	v_fma_f32 v43, -v40, v7, v1
	v_fmac_f32_e32 v7, v43, v41
	v_fma_f32 v1, -v40, v7, v1
	v_div_fmas_f32 v1, v1, v41, v7
	v_pk_mul_f32 v[40:41], v[74:75], v[6:7] op_sel_hi:[1,0]
	v_div_fixup_f32 v26, v1, v26, v42
	s_waitcnt lgkmcnt(0)
; DI float bflo(unsigned u) { return __uint_as_float(u << 16); }
; DI float bfhi(unsigned u) { return __uint_as_float(u & 0xffff0000u); }
; DI float siluf_(float v) { return v / (1.f + __expf(-v)); }
; DI void store_bf4(bf16_t* dst, float a, float b, float c, float d) { u32x2 w; w.x = pk_bf16(a, b); w.y = pk_bf16(c, d); *(u32x2*)dst = w; }
; DI void diff_item(const Params& p, int b, int hh, int qt, float lam, char* smem) {
;     ...
; #pragma unroll
;   for (int db = 0; db < 4; ++db)
; #pragma unroll
;     for (int j = 0; j < 4; ++j) {
;       const int dv = 32 * db + 8 * j + 4 * g;
;       const u32x2 gr = *(const u32x2*)(grow + dv);
;       const f32x4 sl = *(const f32x4*)(slp + dv);
;       store_bf4(yrow + dv, O[0][db][4 * j] * rstd * sl[0] * siluf_(bflo(gr.x)), O[0][db][4 * j + 1] * rstd * sl[1] * siluf_(bfhi(gr.x)),
;                 O[0][db][4 * j + 2] * rstd * sl[2] * siluf_(bflo(gr.y)), O[0][db][4 * j + 3] * rstd * sl[3] * siluf_(bfhi(gr.y)));
	v_pk_mul_f32 v[20:21], v[20:21], v[40:41]
	v_lshlrev_b32_e32 v1, 16, v24
	v_pk_mul_f32 v[4:5], v[4:5], v[20:21]
	v_pk_mul_f32 v[20:21], v[72:73], v[6:7] op_sel_hi:[1,0]
	v_cvt_pk_bf16_f32 v4, v4, v5
	v_pk_mul_f32 v[20:21], v[22:23], v[20:21]
	v_and_b32_e32 v7, 0xffff0000, v24
	v_pk_mul_f32 v[20:21], v[26:27], v[20:21]
	v_mul_f32_e32 v24, 0xbfb8aa3b, v1
	v_cvt_pk_bf16_f32 v5, v20, v21
	global_store_dwordx2 v[2:3], v[4:5], off offset:64
	flat_load_dwordx4 v[20:23], v[14:15] offset:160
	s_nop 0
	global_load_dwordx2 v[4:5], v[136:137], off offset:96
	global_load_dwordx2 v[26:27], v[136:137], off offset:112
	global_load_dwordx2 v[40:41], v[136:137], off offset:128
	v_exp_f32_e32 v42, v24
	v_mul_f32_e32 v24, 0xbfb8aa3b, v7
	v_exp_f32_e32 v43, v24
	s_nop 0
	v_pk_add_f32 v[42:43], v[42:43], 1.0 op_sel_hi:[1,0]
	s_nop 0
	v_div_scale_f32 v24, s[0:1], v43, v43, v7
	v_rcp_f32_e32 v44, v24
	s_nop 0
	v_fma_f32 v45, -v24, v44, 1.0
	v_fmac_f32_e32 v44, v45, v44
	v_div_scale_f32 v45, vcc, v7, v43, v7
	v_mul_f32_e32 v46, v45, v44
	v_fma_f32 v47, -v24, v46, v45
	v_fmac_f32_e32 v46, v47, v44
	v_fma_f32 v24, -v24, v46, v45
	v_div_scale_f32 v45, s[0:1], v42, v42, v1
	v_rcp_f32_e32 v47, v45
	v_div_fmas_f32 v24, v24, v44, v46
	v_lshlrev_b32_e32 v46, 16, v25
	v_div_fixup_f32 v43, v24, v43, v7
	v_mul_f32_e32 v24, 0xbfb8aa3b, v46
	v_mul_f32_e32 v25, 0xbfb8aa3b, v60
	v_fma_f32 v7, -v45, v47, 1.0
	v_exp_f32_e32 v24, v24
	v_exp_f32_e32 v25, v25
	v_fmac_f32_e32 v47, v7, v47
	v_div_scale_f32 v7, vcc, v1, v42, v1
	v_mul_f32_e32 v44, v7, v47
	v_fma_f32 v61, -v45, v44, v7
	v_fmac_f32_e32 v44, v61, v47
	v_pk_add_f32 v[24:25], v[24:25], 1.0 op_sel_hi:[1,0]
	v_fma_f32 v7, -v45, v44, v7
	v_div_scale_f32 v45, s[0:1], v25, v25, v60
	v_rcp_f32_e32 v61, v45
	v_div_fmas_f32 v7, v7, v47, v44
	v_div_fixup_f32 v42, v7, v42, v1
	v_fma_f32 v1, -v45, v61, 1.0
	v_fmac_f32_e32 v61, v1, v61
	v_div_scale_f32 v1, vcc, v60, v25, v60
	v_mul_f32_e32 v7, v1, v61
	v_fma_f32 v44, -v45, v7, v1
	v_fmac_f32_e32 v7, v44, v61
	v_div_scale_f32 v44, s[0:1], v24, v24, v46
	v_fma_f32 v1, -v45, v7, v1
	v_rcp_f32_e32 v45, v44
	v_div_fmas_f32 v1, v1, v61, v7
	v_div_fixup_f32 v25, v1, v25, v60
	v_fma_f32 v1, -v44, v45, 1.0
	v_fmac_f32_e32 v45, v1, v45
	v_div_scale_f32 v1, vcc, v46, v24, v46
	v_mul_f32_e32 v7, v1, v45
	v_fma_f32 v47, -v44, v7, v1
	v_fmac_f32_e32 v7, v47, v45
	v_fma_f32 v1, -v44, v7, v1
	v_div_fmas_f32 v1, v1, v45, v7
	v_pk_mul_f32 v[44:45], v[70:71], v[6:7] op_sel_hi:[1,0]
	v_div_fixup_f32 v24, v1, v24, v46
	s_waitcnt vmcnt(0) lgkmcnt(0)
	v_pk_mul_f32 v[20:21], v[20:21], v[44:45]
	s_nop 0
	v_pk_mul_f32 v[20:21], v[42:43], v[20:21]
	v_pk_mul_f32 v[42:43], v[68:69], v[6:7] op_sel_hi:[1,0]
	v_cvt_pk_bf16_f32 v20, v20, v21
	v_pk_mul_f32 v[22:23], v[22:23], v[42:43]
	v_lshlrev_b32_e32 v1, 16, v4
	v_pk_mul_f32 v[22:23], v[24:25], v[22:23]
	v_and_b32_e32 v4, 0xffff0000, v4
	v_cvt_pk_bf16_f32 v21, v22, v23
	global_store_dwordx2 v[2:3], v[20:21], off offset:80
	flat_load_dwordx4 v[20:23], v[14:15] offset:192
	v_mul_f32_e32 v7, 0xbfb8aa3b, v1
	v_exp_f32_e32 v24, v7
	v_mul_f32_e32 v7, 0xbfb8aa3b, v4
	v_exp_f32_e32 v25, v7
	v_and_b32_e32 v46, 0xffff0000, v5
	v_pk_add_f32 v[24:25], v[24:25], 1.0 op_sel_hi:[1,0]
	s_nop 0
	v_div_scale_f32 v7, s[0:1], v25, v25, v4
	v_rcp_f32_e32 v42, v7
	s_nop 0
	v_fma_f32 v43, -v7, v42, 1.0
	v_fmac_f32_e32 v42, v43, v42
	v_div_scale_f32 v43, vcc, v4, v25, v4
	v_mul_f32_e32 v44, v43, v42
	v_fma_f32 v45, -v7, v44, v43
	v_fmac_f32_e32 v44, v45, v42
	v_fma_f32 v7, -v7, v44, v43
	v_div_scale_f32 v43, s[0:1], v24, v24, v1
	v_rcp_f32_e32 v45, v43
	v_div_fmas_f32 v7, v7, v42, v44
	v_div_fixup_f32 v25, v7, v25, v4
	v_lshlrev_b32_e32 v44, 16, v5
	v_fma_f32 v4, -v43, v45, 1.0
	v_fmac_f32_e32 v45, v4, v45
	v_mul_f32_e32 v4, 0xbfb8aa3b, v44
	v_mul_f32_e32 v5, 0xbfb8aa3b, v46
	v_exp_f32_e32 v4, v4
	v_exp_f32_e32 v5, v5
	v_div_scale_f32 v7, vcc, v1, v24, v1
	v_mul_f32_e32 v42, v7, v45
	v_fma_f32 v47, -v43, v42, v7
	v_fmac_f32_e32 v42, v47, v45
	v_pk_add_f32 v[4:5], v[4:5], 1.0 op_sel_hi:[1,0]
	v_fma_f32 v7, -v43, v42, v7
	v_div_scale_f32 v43, s[0:1], v5, v5, v46
	v_rcp_f32_e32 v47, v43
	v_div_fmas_f32 v7, v7, v45, v42
	v_div_fixup_f32 v24, v7, v24, v1
	v_fma_f32 v1, -v43, v47, 1.0
	v_fmac_f32_e32 v47, v1, v47
	v_div_scale_f32 v1, vcc, v46, v5, v46
	v_mul_f32_e32 v7, v1, v47
	v_fma_f32 v42, -v43, v7, v1
	v_fmac_f32_e32 v7, v42, v47
	v_div_scale_f32 v42, s[0:1], v4, v4, v44
	v_fma_f32 v1, -v43, v7, v1
	v_rcp_f32_e32 v43, v42
	v_div_fmas_f32 v1, v1, v47, v7
	v_div_fixup_f32 v5, v1, v5, v46
	v_fma_f32 v1, -v42, v43, 1.0
	v_fmac_f32_e32 v43, v1, v43
	v_div_scale_f32 v1, vcc, v44, v4, v44
	v_mul_f32_e32 v7, v1, v43
	v_fma_f32 v45, -v42, v7, v1
	v_fmac_f32_e32 v7, v45, v43
	v_fma_f32 v1, -v42, v7, v1
	v_div_fmas_f32 v1, v1, v43, v7
	v_pk_mul_f32 v[42:43], v[66:67], v[6:7] op_sel_hi:[1,0]
	v_div_fixup_f32 v4, v1, v4, v44
	v_lshlrev_b32_e32 v1, 16, v26
	v_lshlrev_b32_e32 v44, 16, v27
	v_and_b32_e32 v27, 0xffff0000, v27
	s_waitcnt vmcnt(0) lgkmcnt(0)
; DI float bflo(unsigned u) { return __uint_as_float(u << 16); }
; DI float bfhi(unsigned u) { return __uint_as_float(u & 0xffff0000u); }
; DI float siluf_(float v) { return v / (1.f + __expf(-v)); }
; DI void store_bf4(bf16_t* dst, float a, float b, float c, float d) { u32x2 w; w.x = pk_bf16(a, b); w.y = pk_bf16(c, d); *(u32x2*)dst = w; }
; DI void diff_item(const Params& p, int b, int hh, int qt, float lam, char* smem) {
;     ...
; #pragma unroll
;   for (int db = 0; db < 4; ++db)
; #pragma unroll
;     for (int j = 0; j < 4; ++j) {
;       const int dv = 32 * db + 8 * j + 4 * g;
;       const u32x2 gr = *(const u32x2*)(grow + dv);
;       const f32x4 sl = *(const f32x4*)(slp + dv);
;       store_bf4(yrow + dv, O[0][db][4 * j] * rstd * sl[0] * siluf_(bflo(gr.x)), O[0][db][4 * j + 1] * rstd * sl[1] * siluf_(bfhi(gr.x)),
;                 O[0][db][4 * j + 2] * rstd * sl[2] * siluf_(bflo(gr.y)), O[0][db][4 * j + 3] * rstd * sl[3] * siluf_(bfhi(gr.y)));
	v_pk_mul_f32 v[20:21], v[20:21], v[42:43]
	s_nop 0
	v_pk_mul_f32 v[20:21], v[24:25], v[20:21]
	v_pk_mul_f32 v[24:25], v[64:65], v[6:7] op_sel_hi:[1,0]
	v_cvt_pk_bf16_f32 v20, v20, v21
	v_pk_mul_f32 v[22:23], v[22:23], v[24:25]
	v_and_b32_e32 v7, 0xffff0000, v26
	v_pk_mul_f32 v[4:5], v[4:5], v[22:23]
	s_nop 0
	v_cvt_pk_bf16_f32 v21, v4, v5
	global_store_dwordx2 v[2:3], v[20:21], off offset:96
	flat_load_dwordx4 v[20:23], v[14:15] offset:224
	v_mul_f32_e32 v4, 0xbfb8aa3b, v1
	v_mul_f32_e32 v5, 0xbfb8aa3b, v7
	v_exp_f32_e32 v4, v4
	v_exp_f32_e32 v5, v5
	s_nop 0
	v_pk_add_f32 v[4:5], v[4:5], 1.0 op_sel_hi:[1,0]
	s_nop 0
	v_div_scale_f32 v24, s[0:1], v5, v5, v7
	v_rcp_f32_e32 v25, v24
	s_nop 0
	v_fma_f32 v26, -v24, v25, 1.0
	v_fmac_f32_e32 v25, v26, v25
	v_div_scale_f32 v26, vcc, v7, v5, v7
	v_mul_f32_e32 v42, v26, v25
	v_fma_f32 v43, -v24, v42, v26
	v_fmac_f32_e32 v42, v43, v25
	v_fma_f32 v24, -v24, v42, v26
	v_div_scale_f32 v26, s[0:1], v4, v4, v1
	v_rcp_f32_e32 v43, v26
	v_div_fmas_f32 v24, v24, v25, v42
	v_div_fixup_f32 v5, v24, v5, v7
	v_mul_f32_e32 v24, 0xbfb8aa3b, v44
	v_mul_f32_e32 v25, 0xbfb8aa3b, v27
	v_fma_f32 v7, -v26, v43, 1.0
	v_exp_f32_e32 v24, v24
	v_exp_f32_e32 v25, v25
	v_fmac_f32_e32 v43, v7, v43
	v_div_scale_f32 v7, vcc, v1, v4, v1
	v_mul_f32_e32 v42, v7, v43
	v_fma_f32 v45, -v26, v42, v7
	v_fmac_f32_e32 v42, v45, v43
	v_pk_add_f32 v[24:25], v[24:25], 1.0 op_sel_hi:[1,0]
	v_fma_f32 v7, -v26, v42, v7
	v_div_scale_f32 v26, s[0:1], v25, v25, v27
	v_rcp_f32_e32 v45, v26
	v_div_fmas_f32 v7, v7, v43, v42
	v_div_fixup_f32 v4, v7, v4, v1
	v_fma_f32 v1, -v26, v45, 1.0
	v_fmac_f32_e32 v45, v1, v45
	v_div_scale_f32 v1, vcc, v27, v25, v27
	v_mul_f32_e32 v7, v1, v45
	v_fma_f32 v42, -v26, v7, v1
	v_fmac_f32_e32 v7, v42, v45
	v_fma_f32 v1, -v26, v7, v1
	v_div_scale_f32 v26, s[0:1], v24, v24, v44
	v_rcp_f32_e32 v42, v26
	v_div_fmas_f32 v1, v1, v45, v7
	v_div_fixup_f32 v25, v1, v25, v27
	v_fma_f32 v1, -v26, v42, 1.0
	v_fmac_f32_e32 v42, v1, v42
	v_div_scale_f32 v1, vcc, v44, v24, v44
	v_mul_f32_e32 v7, v1, v42
	v_fma_f32 v27, -v26, v7, v1
	v_fmac_f32_e32 v7, v27, v42
	v_fma_f32 v1, -v26, v7, v1
	v_pk_mul_f32 v[26:27], v[58:59], v[6:7] op_sel_hi:[1,0]
	v_div_fmas_f32 v1, v1, v42, v7
	v_div_fixup_f32 v24, v1, v24, v44
	v_lshlrev_b32_e32 v1, 16, v40
	v_lshlrev_b32_e32 v44, 16, v41
	v_and_b32_e32 v41, 0xffff0000, v41
	s_waitcnt vmcnt(0) lgkmcnt(0)
	v_pk_mul_f32 v[20:21], v[20:21], v[26:27]
	s_nop 0
	v_pk_mul_f32 v[4:5], v[4:5], v[20:21]
	v_pk_mul_f32 v[20:21], v[56:57], v[6:7] op_sel_hi:[1,0]
	v_cvt_pk_bf16_f32 v4, v4, v5
	v_pk_mul_f32 v[20:21], v[22:23], v[20:21]
	v_and_b32_e32 v7, 0xffff0000, v40
	v_pk_mul_f32 v[20:21], v[24:25], v[20:21]
	global_load_dwordx2 v[24:25], v[136:137], off offset:144
	v_cvt_pk_bf16_f32 v5, v20, v21
	global_store_dwordx2 v[2:3], v[4:5], off offset:112
	flat_load_dwordx4 v[20:23], v[14:15] offset:256
	v_mul_f32_e32 v4, 0xbfb8aa3b, v1
	v_mul_f32_e32 v5, 0xbfb8aa3b, v7
	v_exp_f32_e32 v4, v4
	v_exp_f32_e32 v5, v5
	s_nop 0
	v_pk_add_f32 v[4:5], v[4:5], 1.0 op_sel_hi:[1,0]
	s_nop 0
	v_div_scale_f32 v26, s[0:1], v5, v5, v7
	v_rcp_f32_e32 v27, v26
	s_nop 0
	v_fma_f32 v40, -v26, v27, 1.0
	v_fmac_f32_e32 v27, v40, v27
	v_div_scale_f32 v40, vcc, v7, v5, v7
	v_mul_f32_e32 v42, v40, v27
	v_fma_f32 v43, -v26, v42, v40
	v_fmac_f32_e32 v42, v43, v27
	v_fma_f32 v26, -v26, v42, v40
	v_div_scale_f32 v40, s[0:1], v4, v4, v1
	v_rcp_f32_e32 v43, v40
	v_div_fmas_f32 v26, v26, v27, v42
	v_div_fixup_f32 v5, v26, v5, v7
	v_mul_f32_e32 v26, 0xbfb8aa3b, v44
	v_mul_f32_e32 v27, 0xbfb8aa3b, v41
	v_fma_f32 v7, -v40, v43, 1.0
	v_exp_f32_e32 v26, v26
	v_exp_f32_e32 v27, v27
	v_fmac_f32_e32 v43, v7, v43
	v_div_scale_f32 v7, vcc, v1, v4, v1
	v_mul_f32_e32 v42, v7, v43
	v_fma_f32 v45, -v40, v42, v7
	v_fmac_f32_e32 v42, v45, v43
	v_pk_add_f32 v[26:27], v[26:27], 1.0 op_sel_hi:[1,0]
	v_fma_f32 v7, -v40, v42, v7
	v_div_scale_f32 v40, s[0:1], v27, v27, v41
	v_rcp_f32_e32 v45, v40
	v_div_fmas_f32 v7, v7, v43, v42
	v_div_fixup_f32 v4, v7, v4, v1
	v_fma_f32 v1, -v40, v45, 1.0
	v_fmac_f32_e32 v45, v1, v45
	v_div_scale_f32 v1, vcc, v41, v27, v41
	v_mul_f32_e32 v7, v1, v45
	v_fma_f32 v42, -v40, v7, v1
	v_fmac_f32_e32 v7, v42, v45
	v_fma_f32 v1, -v40, v7, v1
	v_div_scale_f32 v40, s[0:1], v26, v26, v44
	v_rcp_f32_e32 v42, v40
	v_div_fmas_f32 v1, v1, v45, v7
	v_div_fixup_f32 v27, v1, v27, v41
	v_fma_f32 v1, -v40, v42, 1.0
	v_fmac_f32_e32 v42, v1, v42
	v_div_scale_f32 v1, vcc, v44, v26, v44
	v_mul_f32_e32 v7, v1, v42
	v_fma_f32 v41, -v40, v7, v1
	v_fmac_f32_e32 v7, v41, v42
	v_fma_f32 v1, -v40, v7, v1
	v_pk_mul_f32 v[40:41], v[54:55], v[6:7] op_sel_hi:[1,0]
	v_div_fmas_f32 v1, v1, v42, v7
	v_div_fixup_f32 v26, v1, v26, v44
	s_waitcnt vmcnt(0)
	v_lshlrev_b32_e32 v1, 16, v24
	s_waitcnt lgkmcnt(0)
; DI float bflo(unsigned u) { return __uint_as_float(u << 16); }
; DI float bfhi(unsigned u) { return __uint_as_float(u & 0xffff0000u); }
; DI float siluf_(float v) { return v / (1.f + __expf(-v)); }
; DI void store_bf4(bf16_t* dst, float a, float b, float c, float d) { u32x2 w; w.x = pk_bf16(a, b); w.y = pk_bf16(c, d); *(u32x2*)dst = w; }
; DI void diff_item(const Params& p, int b, int hh, int qt, float lam, char* smem) {
;     ...
; #pragma unroll
;   for (int db = 0; db < 4; ++db)
; #pragma unroll
;     for (int j = 0; j < 4; ++j) {
;       const int dv = 32 * db + 8 * j + 4 * g;
;       const u32x2 gr = *(const u32x2*)(grow + dv);
;       const f32x4 sl = *(const f32x4*)(slp + dv);
;       store_bf4(yrow + dv, O[0][db][4 * j] * rstd * sl[0] * siluf_(bflo(gr.x)), O[0][db][4 * j + 1] * rstd * sl[1] * siluf_(bfhi(gr.x)),
;                 O[0][db][4 * j + 2] * rstd * sl[2] * siluf_(bflo(gr.y)), O[0][db][4 * j + 3] * rstd * sl[3] * siluf_(bfhi(gr.y)));
	v_pk_mul_f32 v[20:21], v[20:21], v[40:41]
	s_nop 0
	v_pk_mul_f32 v[4:5], v[4:5], v[20:21]
	v_pk_mul_f32 v[20:21], v[52:53], v[6:7] op_sel_hi:[1,0]
	v_cvt_pk_bf16_f32 v4, v4, v5
	v_pk_mul_f32 v[20:21], v[22:23], v[20:21]
	v_and_b32_e32 v7, 0xffff0000, v24
	v_pk_mul_f32 v[20:21], v[26:27], v[20:21]
	v_mul_f32_e32 v24, 0xbfb8aa3b, v1
	v_cvt_pk_bf16_f32 v5, v20, v21
	global_store_dwordx2 v[2:3], v[4:5], off offset:128
	flat_load_dwordx4 v[20:23], v[14:15] offset:288
	s_nop 0
	global_load_dwordx2 v[4:5], v[136:137], off offset:160
	global_load_dwordx2 v[26:27], v[136:137], off offset:176
	global_load_dwordx2 v[40:41], v[136:137], off offset:192
	v_exp_f32_e32 v42, v24
	v_mul_f32_e32 v24, 0xbfb8aa3b, v7
	v_exp_f32_e32 v43, v24
	v_and_b32_e32 v52, 0xffff0000, v25
	v_pk_add_f32 v[42:43], v[42:43], 1.0 op_sel_hi:[1,0]
	s_nop 0
	v_div_scale_f32 v24, s[0:1], v43, v43, v7
	v_rcp_f32_e32 v44, v24
	s_nop 0
	v_fma_f32 v45, -v24, v44, 1.0
	v_fmac_f32_e32 v44, v45, v44
	v_div_scale_f32 v45, vcc, v7, v43, v7
	v_mul_f32_e32 v46, v45, v44
	v_fma_f32 v47, -v24, v46, v45
	v_fmac_f32_e32 v46, v47, v44
	v_fma_f32 v24, -v24, v46, v45
	v_div_scale_f32 v45, s[0:1], v42, v42, v1
	v_rcp_f32_e32 v47, v45
	v_div_fmas_f32 v24, v24, v44, v46
	v_lshlrev_b32_e32 v46, 16, v25
	v_div_fixup_f32 v43, v24, v43, v7
	v_mul_f32_e32 v24, 0xbfb8aa3b, v46
	v_mul_f32_e32 v25, 0xbfb8aa3b, v52
	v_fma_f32 v7, -v45, v47, 1.0
	v_exp_f32_e32 v24, v24
	v_exp_f32_e32 v25, v25
	v_fmac_f32_e32 v47, v7, v47
	v_div_scale_f32 v7, vcc, v1, v42, v1
	v_mul_f32_e32 v44, v7, v47
	v_fma_f32 v53, -v45, v44, v7
	v_fmac_f32_e32 v44, v53, v47
	v_pk_add_f32 v[24:25], v[24:25], 1.0 op_sel_hi:[1,0]
	v_fma_f32 v7, -v45, v44, v7
	v_div_scale_f32 v45, s[0:1], v25, v25, v52
	v_rcp_f32_e32 v53, v45
	v_div_fmas_f32 v7, v7, v47, v44
	v_div_fixup_f32 v42, v7, v42, v1
	v_fma_f32 v1, -v45, v53, 1.0
	v_fmac_f32_e32 v53, v1, v53
	v_div_scale_f32 v1, vcc, v52, v25, v52
	v_mul_f32_e32 v7, v1, v53
	v_fma_f32 v44, -v45, v7, v1
	v_fmac_f32_e32 v7, v44, v53
	v_div_scale_f32 v44, s[0:1], v24, v24, v46
	v_fma_f32 v1, -v45, v7, v1
	v_rcp_f32_e32 v45, v44
	v_div_fmas_f32 v1, v1, v53, v7
	v_div_fixup_f32 v25, v1, v25, v52
	v_fma_f32 v1, -v44, v45, 1.0
	v_fmac_f32_e32 v45, v1, v45
	v_div_scale_f32 v1, vcc, v46, v24, v46
	v_mul_f32_e32 v7, v1, v45
	v_fma_f32 v47, -v44, v7, v1
	v_fmac_f32_e32 v7, v47, v45
	v_fma_f32 v1, -v44, v7, v1
	v_div_fmas_f32 v1, v1, v45, v7
	v_pk_mul_f32 v[44:45], v[50:51], v[6:7] op_sel_hi:[1,0]
	v_div_fixup_f32 v24, v1, v24, v46
	s_waitcnt vmcnt(0) lgkmcnt(0)
	v_pk_mul_f32 v[20:21], v[20:21], v[44:45]
	s_nop 0
	v_pk_mul_f32 v[20:21], v[42:43], v[20:21]
	v_pk_mul_f32 v[42:43], v[48:49], v[6:7] op_sel_hi:[1,0]
	v_cvt_pk_bf16_f32 v20, v20, v21
	v_pk_mul_f32 v[22:23], v[22:23], v[42:43]
	v_lshlrev_b32_e32 v1, 16, v4
	v_pk_mul_f32 v[22:23], v[24:25], v[22:23]
	v_and_b32_e32 v4, 0xffff0000, v4
	v_cvt_pk_bf16_f32 v21, v22, v23
	global_store_dwordx2 v[2:3], v[20:21], off offset:144
	flat_load_dwordx4 v[20:23], v[14:15] offset:320
	v_mul_f32_e32 v7, 0xbfb8aa3b, v1
	v_exp_f32_e32 v24, v7
	v_mul_f32_e32 v7, 0xbfb8aa3b, v4
	v_exp_f32_e32 v25, v7
	v_and_b32_e32 v46, 0xffff0000, v5
	v_pk_add_f32 v[24:25], v[24:25], 1.0 op_sel_hi:[1,0]
	s_nop 0
	v_div_scale_f32 v7, s[0:1], v25, v25, v4
	v_rcp_f32_e32 v42, v7
	s_nop 0
	v_fma_f32 v43, -v7, v42, 1.0
	v_fmac_f32_e32 v42, v43, v42
	v_div_scale_f32 v43, vcc, v4, v25, v4
	v_mul_f32_e32 v44, v43, v42
	v_fma_f32 v45, -v7, v44, v43
	v_fmac_f32_e32 v44, v45, v42
	v_fma_f32 v7, -v7, v44, v43
	v_div_scale_f32 v43, s[0:1], v24, v24, v1
	v_rcp_f32_e32 v45, v43
	v_div_fmas_f32 v7, v7, v42, v44
	v_div_fixup_f32 v25, v7, v25, v4
	v_lshlrev_b32_e32 v44, 16, v5
	v_fma_f32 v4, -v43, v45, 1.0
	v_fmac_f32_e32 v45, v4, v45
	v_mul_f32_e32 v4, 0xbfb8aa3b, v44
	v_mul_f32_e32 v5, 0xbfb8aa3b, v46
	v_exp_f32_e32 v4, v4
	v_exp_f32_e32 v5, v5
	v_div_scale_f32 v7, vcc, v1, v24, v1
	v_mul_f32_e32 v42, v7, v45
	v_fma_f32 v47, -v43, v42, v7
	v_fmac_f32_e32 v42, v47, v45
	v_pk_add_f32 v[4:5], v[4:5], 1.0 op_sel_hi:[1,0]
	v_fma_f32 v7, -v43, v42, v7
	v_div_scale_f32 v43, s[0:1], v5, v5, v46
	v_rcp_f32_e32 v47, v43
	v_div_fmas_f32 v7, v7, v45, v42
	v_div_fixup_f32 v24, v7, v24, v1
	v_fma_f32 v1, -v43, v47, 1.0
	v_fmac_f32_e32 v47, v1, v47
	v_div_scale_f32 v1, vcc, v46, v5, v46
	v_mul_f32_e32 v7, v1, v47
	v_fma_f32 v42, -v43, v7, v1
	v_fmac_f32_e32 v7, v42, v47
	v_div_scale_f32 v42, s[0:1], v4, v4, v44
	v_fma_f32 v1, -v43, v7, v1
	v_rcp_f32_e32 v43, v42
	v_div_fmas_f32 v1, v1, v47, v7
	v_div_fixup_f32 v5, v1, v5, v46
	v_fma_f32 v1, -v42, v43, 1.0
	v_fmac_f32_e32 v43, v1, v43
	v_div_scale_f32 v1, vcc, v44, v4, v44
	v_mul_f32_e32 v7, v1, v43
	v_fma_f32 v45, -v42, v7, v1
	v_fmac_f32_e32 v7, v45, v43
	v_pk_mul_f32 v[38:39], v[38:39], v[6:7] op_sel_hi:[1,0]
	v_fma_f32 v1, -v42, v7, v1
	v_div_fmas_f32 v1, v1, v43, v7
	v_div_fixup_f32 v4, v1, v4, v44
	v_lshlrev_b32_e32 v1, 16, v26
	s_waitcnt vmcnt(0) lgkmcnt(0)
	v_pk_mul_f32 v[20:21], v[20:21], v[38:39]
	s_nop 0
	v_pk_mul_f32 v[20:21], v[24:25], v[20:21]
	v_pk_mul_f32 v[24:25], v[36:37], v[6:7] op_sel_hi:[1,0]
	v_cvt_pk_bf16_f32 v20, v20, v21
	v_pk_mul_f32 v[22:23], v[22:23], v[24:25]
	v_and_b32_e32 v7, 0xffff0000, v26
	v_pk_mul_f32 v[4:5], v[4:5], v[22:23]
	v_pk_mul_f32 v[24:25], v[34:35], v[6:7] op_sel_hi:[1,0]
	v_cvt_pk_bf16_f32 v21, v4, v5
	global_store_dwordx2 v[2:3], v[20:21], off offset:160
	flat_load_dwordx4 v[20:23], v[14:15] offset:352
	v_mul_f32_e32 v4, 0xbfb8aa3b, v1
	v_mul_f32_e32 v5, 0xbfb8aa3b, v7
	v_exp_f32_e32 v4, v4
	v_exp_f32_e32 v5, v5
	s_waitcnt vmcnt(0) lgkmcnt(0)
; DI float bflo(unsigned u) { return __uint_as_float(u << 16); }
; DI float bfhi(unsigned u) { return __uint_as_float(u & 0xffff0000u); }
; DI float siluf_(float v) { return v / (1.f + __expf(-v)); }
; DI void store_bf4(bf16_t* dst, float a, float b, float c, float d) { u32x2 w; w.x = pk_bf16(a, b); w.y = pk_bf16(c, d); *(u32x2*)dst = w; }
; DI void diff_item(const Params& p, int b, int hh, int qt, float lam, char* smem) {
;     ...
; #pragma unroll
;   for (int db = 0; db < 4; ++db)
; #pragma unroll
;     for (int j = 0; j < 4; ++j) {
;       const int dv = 32 * db + 8 * j + 4 * g;
;       const u32x2 gr = *(const u32x2*)(grow + dv);
;       const f32x4 sl = *(const f32x4*)(slp + dv);
;       store_bf4(yrow + dv, O[0][db][4 * j] * rstd * sl[0] * siluf_(bflo(gr.x)), O[0][db][4 * j + 1] * rstd * sl[1] * siluf_(bfhi(gr.x)),
;                 O[0][db][4 * j + 2] * rstd * sl[2] * siluf_(bflo(gr.y)), O[0][db][4 * j + 3] * rstd * sl[3] * siluf_(bfhi(gr.y)));
	v_pk_mul_f32 v[20:21], v[20:21], v[24:25]
	v_pk_add_f32 v[4:5], v[4:5], 1.0 op_sel_hi:[1,0]
	s_nop 0
	v_div_scale_f32 v26, s[0:1], v5, v5, v7
	v_rcp_f32_e32 v36, v26
	s_nop 0
	v_fma_f32 v24, -v26, v36, 1.0
	v_fmac_f32_e32 v36, v24, v36
	v_div_scale_f32 v24, vcc, v7, v5, v7
	v_mul_f32_e32 v25, v24, v36
	v_fma_f32 v34, -v26, v25, v24
	v_fmac_f32_e32 v25, v34, v36
	v_fma_f32 v24, -v26, v25, v24
	v_div_scale_f32 v26, s[0:1], v4, v4, v1
	v_rcp_f32_e32 v34, v26
	v_div_fmas_f32 v24, v24, v36, v25
	v_div_fixup_f32 v5, v24, v5, v7
	v_fma_f32 v7, -v26, v34, 1.0
	v_fmac_f32_e32 v34, v7, v34
	v_div_scale_f32 v7, vcc, v1, v4, v1
	v_mul_f32_e32 v35, v7, v34
	v_fma_f32 v24, -v26, v35, v7
	v_fmac_f32_e32 v35, v24, v34
	v_fma_f32 v7, -v26, v35, v7
	v_lshlrev_b32_e32 v26, 16, v27
	v_and_b32_e32 v27, 0xffff0000, v27
	v_mul_f32_e32 v24, 0xbfb8aa3b, v26
	v_mul_f32_e32 v25, 0xbfb8aa3b, v27
	v_exp_f32_e32 v24, v24
	v_exp_f32_e32 v25, v25
	v_div_fmas_f32 v7, v7, v34, v35
	v_div_fixup_f32 v4, v7, v4, v1
	v_pk_mul_f32 v[4:5], v[4:5], v[20:21]
	v_pk_add_f32 v[24:25], v[24:25], 1.0 op_sel_hi:[1,0]
	v_cvt_pk_bf16_f32 v4, v4, v5
	v_div_scale_f32 v1, s[0:1], v25, v25, v27
	v_rcp_f32_e32 v7, v1
	s_nop 0
	v_pk_mul_f32 v[20:21], v[32:33], v[6:7] op_sel_hi:[1,0]
	s_nop 0
	v_pk_mul_f32 v[20:21], v[22:23], v[20:21]
	v_fma_f32 v22, -v1, v7, 1.0
	v_fmac_f32_e32 v7, v22, v7
	v_div_scale_f32 v22, vcc, v27, v25, v27
	v_mul_f32_e32 v23, v22, v7
	v_fma_f32 v32, -v1, v23, v22
	v_fmac_f32_e32 v23, v32, v7
	v_fma_f32 v1, -v1, v23, v22
	v_div_scale_f32 v22, s[0:1], v24, v24, v26
	v_rcp_f32_e32 v32, v22
	v_div_fmas_f32 v1, v1, v7, v23
	v_div_fixup_f32 v23, v1, v25, v27
	v_fma_f32 v1, -v22, v32, 1.0
	v_fmac_f32_e32 v32, v1, v32
	v_div_scale_f32 v1, vcc, v26, v24, v26
	v_mul_f32_e32 v7, v1, v32
	v_fma_f32 v25, -v22, v7, v1
	v_fmac_f32_e32 v7, v25, v32
	v_fma_f32 v1, -v22, v7, v1
	v_div_fmas_f32 v1, v1, v32, v7
	v_div_fixup_f32 v22, v1, v24, v26
	v_pk_mul_f32 v[20:21], v[22:23], v[20:21]
	v_lshlrev_b32_e32 v1, 16, v40
	v_cvt_pk_bf16_f32 v5, v20, v21
	global_store_dwordx2 v[2:3], v[4:5], off offset:176
	flat_load_dwordx4 v[20:23], v[14:15] offset:384
	v_and_b32_e32 v7, 0xffff0000, v40
	v_mul_f32_e32 v4, 0xbfb8aa3b, v1
	v_mul_f32_e32 v5, 0xbfb8aa3b, v7
	v_exp_f32_e32 v4, v4
	v_exp_f32_e32 v5, v5
	v_pk_mul_f32 v[24:25], v[30:31], v[6:7] op_sel_hi:[1,0]
	v_and_b32_e32 v31, 0xffff0000, v41
	v_pk_add_f32 v[4:5], v[4:5], 1.0 op_sel_hi:[1,0]
	s_nop 0
	v_div_scale_f32 v26, s[0:1], v5, v5, v7
	v_rcp_f32_e32 v27, v26
	s_waitcnt vmcnt(0) lgkmcnt(0)
	v_pk_mul_f32 v[20:21], v[20:21], v[24:25]
	v_fma_f32 v24, -v26, v27, 1.0
	v_fmac_f32_e32 v27, v24, v27
	v_div_scale_f32 v24, vcc, v7, v5, v7
	v_mul_f32_e32 v25, v24, v27
	v_fma_f32 v30, -v26, v25, v24
	v_fmac_f32_e32 v25, v30, v27
	v_fma_f32 v24, -v26, v25, v24
	v_div_scale_f32 v26, s[0:1], v4, v4, v1
	v_rcp_f32_e32 v30, v26
	v_div_fmas_f32 v24, v24, v27, v25
	v_div_fixup_f32 v5, v24, v5, v7
	v_mul_f32_e32 v25, 0xbfb8aa3b, v31
	v_fma_f32 v7, -v26, v30, 1.0
	v_fmac_f32_e32 v30, v7, v30
	v_div_scale_f32 v7, vcc, v1, v4, v1
	v_mul_f32_e32 v27, v7, v30
	v_fma_f32 v24, -v26, v27, v7
	v_fmac_f32_e32 v27, v24, v30
	v_fma_f32 v7, -v26, v27, v7
	v_lshlrev_b32_e32 v26, 16, v41
	v_mul_f32_e32 v24, 0xbfb8aa3b, v26
	v_exp_f32_e32 v24, v24
	v_exp_f32_e32 v25, v25
	v_div_fmas_f32 v7, v7, v30, v27
	v_div_fixup_f32 v4, v7, v4, v1
	v_pk_mul_f32 v[4:5], v[4:5], v[20:21]
	v_pk_add_f32 v[24:25], v[24:25], 1.0 op_sel_hi:[1,0]
	v_cvt_pk_bf16_f32 v4, v4, v5
	v_div_scale_f32 v1, s[0:1], v25, v25, v31
	v_rcp_f32_e32 v7, v1
	s_nop 0
	v_fma_f32 v20, -v1, v7, 1.0
	v_pk_mul_f32 v[18:19], v[18:19], v[6:7] op_sel_hi:[1,0]
	v_fmac_f32_e32 v7, v20, v7
	v_div_scale_f32 v20, vcc, v31, v25, v31
	v_mul_f32_e32 v21, v20, v7
	v_pk_mul_f32 v[18:19], v[22:23], v[18:19]
	v_fma_f32 v22, -v1, v21, v20
	v_fmac_f32_e32 v21, v22, v7
	v_fma_f32 v1, -v1, v21, v20
	v_div_scale_f32 v20, s[0:1], v24, v24, v26
	v_rcp_f32_e32 v27, v20
	global_load_dwordx2 v[22:23], v[136:137], off offset:208
	v_div_fmas_f32 v1, v1, v7, v21
	v_div_fixup_f32 v21, v1, v25, v31
	v_fma_f32 v1, -v20, v27, 1.0
	v_fmac_f32_e32 v27, v1, v27
	v_div_scale_f32 v1, vcc, v26, v24, v26
	v_mul_f32_e32 v7, v1, v27
	v_fma_f32 v25, -v20, v7, v1
	v_fmac_f32_e32 v7, v25, v27
	v_fma_f32 v1, -v20, v7, v1
	v_div_fmas_f32 v1, v1, v27, v7
	v_div_fixup_f32 v20, v1, v24, v26
	v_pk_mul_f32 v[18:19], v[20:21], v[18:19]
	s_waitcnt vmcnt(0)
	v_lshlrev_b32_e32 v1, 16, v22
	v_cvt_pk_bf16_f32 v5, v18, v19
	global_store_dwordx2 v[2:3], v[4:5], off offset:192
	flat_load_dwordx4 v[18:21], v[14:15] offset:416
	s_nop 0
	global_load_dwordx2 v[4:5], v[136:137], off offset:224
	v_and_b32_e32 v7, 0xffff0000, v22
	v_mul_f32_e32 v22, 0xbfb8aa3b, v1
	v_exp_f32_e32 v24, v22
	v_mul_f32_e32 v22, 0xbfb8aa3b, v7
	v_exp_f32_e32 v25, v22
	v_pk_mul_f32 v[16:17], v[16:17], v[6:7] op_sel_hi:[1,0]
	v_pk_add_f32 v[24:25], v[24:25], 1.0 op_sel_hi:[1,0]
	s_nop 0
	v_div_scale_f32 v22, s[0:1], v25, v25, v7
	v_rcp_f32_e32 v26, v22
	s_waitcnt vmcnt(0) lgkmcnt(0)
; DI float bflo(unsigned u) { return __uint_as_float(u << 16); }
; DI float bfhi(unsigned u) { return __uint_as_float(u & 0xffff0000u); }
; DI float siluf_(float v) { return v / (1.f + __expf(-v)); }
; DI void store_bf4(bf16_t* dst, float a, float b, float c, float d) { u32x2 w; w.x = pk_bf16(a, b); w.y = pk_bf16(c, d); *(u32x2*)dst = w; }
; DI void diff_item(const Params& p, int b, int hh, int qt, float lam, char* smem) {
;     ...
; #pragma unroll
;   for (int db = 0; db < 4; ++db)
; #pragma unroll
;     for (int j = 0; j < 4; ++j) {
;       const int dv = 32 * db + 8 * j + 4 * g;
;       const u32x2 gr = *(const u32x2*)(grow + dv);
;       const f32x4 sl = *(const f32x4*)(slp + dv);
;       store_bf4(yrow + dv, O[0][db][4 * j] * rstd * sl[0] * siluf_(bflo(gr.x)), O[0][db][4 * j + 1] * rstd * sl[1] * siluf_(bfhi(gr.x)),
;                 O[0][db][4 * j + 2] * rstd * sl[2] * siluf_(bflo(gr.y)), O[0][db][4 * j + 3] * rstd * sl[3] * siluf_(bfhi(gr.y)));
	v_pk_mul_f32 v[16:17], v[18:19], v[16:17]
	v_fma_f32 v18, -v22, v26, 1.0
	v_fmac_f32_e32 v26, v18, v26
	v_div_scale_f32 v18, vcc, v7, v25, v7
	v_mul_f32_e32 v19, v18, v26
	v_fma_f32 v27, -v22, v19, v18
	v_fmac_f32_e32 v19, v27, v26
	v_fma_f32 v18, -v22, v19, v18
	v_div_scale_f32 v22, s[0:1], v24, v24, v1
	v_rcp_f32_e32 v27, v22
	v_div_fmas_f32 v18, v18, v26, v19
	v_div_fixup_f32 v19, v18, v25, v7
	v_and_b32_e32 v26, 0xffff0000, v23
	v_fma_f32 v7, -v22, v27, 1.0
	v_fmac_f32_e32 v27, v7, v27
	v_div_scale_f32 v7, vcc, v1, v24, v1
	v_mul_f32_e32 v18, v7, v27
	v_fma_f32 v25, -v22, v18, v7
	v_fmac_f32_e32 v18, v25, v27
	v_lshlrev_b32_e32 v25, 16, v23
	v_fma_f32 v7, -v22, v18, v7
	v_mul_f32_e32 v22, 0xbfb8aa3b, v25
	v_mul_f32_e32 v23, 0xbfb8aa3b, v26
	v_exp_f32_e32 v22, v22
	v_exp_f32_e32 v23, v23
	v_div_fmas_f32 v7, v7, v27, v18
	v_div_fixup_f32 v18, v7, v24, v1
	v_pk_mul_f32 v[16:17], v[18:19], v[16:17]
	v_pk_add_f32 v[22:23], v[22:23], 1.0 op_sel_hi:[1,0]
	v_cvt_pk_bf16_f32 v16, v16, v17
	v_div_scale_f32 v1, s[0:1], v23, v23, v26
	v_rcp_f32_e32 v7, v1
	s_nop 0
	v_fma_f32 v18, -v1, v7, 1.0
	v_pk_mul_f32 v[12:13], v[12:13], v[6:7] op_sel_hi:[1,0]
	v_fmac_f32_e32 v7, v18, v7
	v_div_scale_f32 v18, vcc, v26, v23, v26
	v_mul_f32_e32 v19, v18, v7
	v_pk_mul_f32 v[12:13], v[20:21], v[12:13]
	v_fma_f32 v20, -v1, v19, v18
	v_fmac_f32_e32 v19, v20, v7
	v_fma_f32 v1, -v1, v19, v18
	v_div_scale_f32 v18, s[0:1], v22, v22, v25
	v_rcp_f32_e32 v20, v18
	v_div_fmas_f32 v1, v1, v7, v19
	v_div_fixup_f32 v19, v1, v23, v26
	v_fma_f32 v1, -v18, v20, 1.0
	v_fmac_f32_e32 v20, v1, v20
	v_div_scale_f32 v1, vcc, v25, v22, v25
	v_mul_f32_e32 v7, v1, v20
	v_fma_f32 v21, -v18, v7, v1
	v_fmac_f32_e32 v7, v21, v20
	v_fma_f32 v1, -v18, v7, v1
	v_div_fmas_f32 v1, v1, v20, v7
	v_div_fixup_f32 v18, v1, v22, v25
	v_pk_mul_f32 v[12:13], v[18:19], v[12:13]
	v_lshlrev_b32_e32 v1, 16, v4
	v_cvt_pk_bf16_f32 v17, v12, v13
	global_store_dwordx2 v[2:3], v[16:17], off offset:208
	flat_load_dwordx4 v[16:19], v[14:15] offset:448
	v_and_b32_e32 v4, 0xffff0000, v4
	v_mul_f32_e32 v7, 0xbfb8aa3b, v1
	v_exp_f32_e32 v12, v7
	v_mul_f32_e32 v7, 0xbfb8aa3b, v4
	v_exp_f32_e32 v13, v7
	s_nop 0
	v_pk_add_f32 v[12:13], v[12:13], 1.0 op_sel_hi:[1,0]
	s_nop 0
	v_div_scale_f32 v7, s[0:1], v13, v13, v4
	v_rcp_f32_e32 v20, v7
	v_pk_mul_f32 v[10:11], v[10:11], v[6:7] op_sel_hi:[1,0]
	s_waitcnt vmcnt(0) lgkmcnt(0)
	v_pk_mul_f32 v[10:11], v[16:17], v[10:11]
	v_fma_f32 v16, -v7, v20, 1.0
	v_fmac_f32_e32 v20, v16, v20
	v_div_scale_f32 v16, vcc, v4, v13, v4
	v_mul_f32_e32 v17, v16, v20
	v_fma_f32 v21, -v7, v17, v16
	v_fmac_f32_e32 v17, v21, v20
	v_fma_f32 v7, -v7, v17, v16
	v_div_scale_f32 v16, s[0:1], v12, v12, v1
	v_rcp_f32_e32 v21, v16
	v_div_fmas_f32 v7, v7, v20, v17
	v_div_fixup_f32 v13, v7, v13, v4
	v_and_b32_e32 v20, 0xffff0000, v5
	v_fma_f32 v4, -v16, v21, 1.0
	v_fmac_f32_e32 v21, v4, v21
	v_div_scale_f32 v4, vcc, v1, v12, v1
	v_mul_f32_e32 v7, v4, v21
	v_fma_f32 v17, -v16, v7, v4
	v_fmac_f32_e32 v7, v17, v21
	v_lshlrev_b32_e32 v17, 16, v5
	v_fma_f32 v16, -v16, v7, v4
	v_mul_f32_e32 v4, 0xbfb8aa3b, v17
	v_mul_f32_e32 v5, 0xbfb8aa3b, v20
	v_exp_f32_e32 v4, v4
	v_exp_f32_e32 v5, v5
	v_div_fmas_f32 v7, v16, v21, v7
	v_div_fixup_f32 v12, v7, v12, v1
	v_pk_mul_f32 v[10:11], v[12:13], v[10:11]
	v_pk_add_f32 v[4:5], v[4:5], 1.0 op_sel_hi:[1,0]
	s_nop 0
	v_div_scale_f32 v1, s[0:1], v5, v5, v20
	v_rcp_f32_e32 v7, v1
	s_nop 0
	v_fma_f32 v12, -v1, v7, 1.0
	v_pk_mul_f32 v[8:9], v[8:9], v[6:7] op_sel_hi:[1,0]
	v_fmac_f32_e32 v7, v12, v7
	v_div_scale_f32 v12, vcc, v20, v5, v20
	v_mul_f32_e32 v13, v12, v7
	v_fma_f32 v16, -v1, v13, v12
	v_fmac_f32_e32 v13, v16, v7
	v_fma_f32 v1, -v1, v13, v12
	v_div_scale_f32 v12, s[0:1], v4, v4, v17
	v_rcp_f32_e32 v16, v12
	v_div_fmas_f32 v1, v1, v7, v13
	v_div_fixup_f32 v5, v1, v5, v20
	v_pk_mul_f32 v[8:9], v[18:19], v[8:9]
	v_fma_f32 v1, -v12, v16, 1.0
	v_fmac_f32_e32 v16, v1, v16
	v_div_scale_f32 v1, vcc, v17, v4, v17
	v_mul_f32_e32 v7, v1, v16
	v_fma_f32 v13, -v12, v7, v1
	v_fmac_f32_e32 v7, v13, v16
	v_fma_f32 v1, -v12, v7, v1
	v_div_fmas_f32 v1, v1, v16, v7
	v_div_fixup_f32 v4, v1, v4, v17
	v_pk_mul_f32 v[4:5], v[4:5], v[8:9]
	v_cvt_pk_bf16_f32 v8, v10, v11
	v_cvt_pk_bf16_f32 v9, v4, v5
	global_store_dwordx2 v[2:3], v[8:9], off offset:224
	flat_load_dwordx4 v[8:11], v[14:15] offset:480
	v_lshlrev_b32_e32 v1, 16, v142
	v_and_b32_e32 v7, 0xffff0000, v142
	v_mul_f32_e32 v4, 0xbfb8aa3b, v1
	v_mul_f32_e32 v5, 0xbfb8aa3b, v7
	v_exp_f32_e32 v4, v4
	v_exp_f32_e32 v5, v5
	v_pk_mul_f32 v[12:13], v[132:133], v[6:7] op_sel_hi:[1,0]
	v_and_b32_e32 v17, 0xffff0000, v143
	v_pk_add_f32 v[4:5], v[4:5], 1.0 op_sel_hi:[1,0]
	s_nop 0
	v_div_scale_f32 v14, s[0:1], v5, v5, v7
	v_rcp_f32_e32 v15, v14
	s_waitcnt vmcnt(0) lgkmcnt(0)
	v_pk_mul_f32 v[8:9], v[8:9], v[12:13]
	v_fma_f32 v12, -v14, v15, 1.0
	v_fmac_f32_e32 v15, v12, v15
	v_div_scale_f32 v12, vcc, v7, v5, v7
	v_mul_f32_e32 v13, v12, v15
	v_fma_f32 v16, -v14, v13, v12
	v_fmac_f32_e32 v13, v16, v15
	v_fma_f32 v12, -v14, v13, v12
	v_div_scale_f32 v14, s[0:1], v4, v4, v1
	v_rcp_f32_e32 v16, v14
	v_div_fmas_f32 v12, v12, v15, v13
	v_div_fixup_f32 v5, v12, v5, v7
	v_mul_f32_e32 v13, 0xbfb8aa3b, v17
	v_fma_f32 v7, -v14, v16, 1.0
	v_fmac_f32_e32 v16, v7, v16
	v_div_scale_f32 v7, vcc, v1, v4, v1
	v_mul_f32_e32 v15, v7, v16
	v_fma_f32 v12, -v14, v15, v7
	v_fmac_f32_e32 v15, v12, v16
	v_fma_f32 v7, -v14, v15, v7
	v_lshlrev_b32_e32 v14, 16, v143
	v_mul_f32_e32 v12, 0xbfb8aa3b, v14
	v_exp_f32_e32 v12, v12
	v_exp_f32_e32 v13, v13
	v_div_fmas_f32 v7, v7, v16, v15
	v_div_fixup_f32 v4, v7, v4, v1
	v_pk_mul_f32 v[4:5], v[4:5], v[8:9]
	v_pk_add_f32 v[12:13], v[12:13], 1.0 op_sel_hi:[1,0]
	v_pk_mul_f32 v[6:7], v[28:29], v[6:7] op_sel_hi:[1,0]
	v_div_scale_f32 v1, s[0:1], v13, v13, v17
	v_rcp_f32_e32 v15, v1
	v_pk_mul_f32 v[6:7], v[10:11], v[6:7]
	v_cvt_pk_bf16_f32 v4, v4, v5
	v_fma_f32 v8, -v1, v15, 1.0
	v_fmac_f32_e32 v15, v8, v15
	v_div_scale_f32 v8, vcc, v17, v13, v17
	v_mul_f32_e32 v9, v8, v15
	v_fma_f32 v10, -v1, v9, v8
	v_fmac_f32_e32 v9, v10, v15
	v_fma_f32 v1, -v1, v9, v8
	v_div_scale_f32 v8, s[0:1], v12, v12, v14
	v_rcp_f32_e32 v10, v8
	v_div_fmas_f32 v1, v1, v15, v9
	v_div_fixup_f32 v9, v1, v13, v17
	v_fma_f32 v1, -v8, v10, 1.0
	v_fmac_f32_e32 v10, v1, v10
	v_div_scale_f32 v1, vcc, v14, v12, v14
	v_mul_f32_e32 v11, v1, v10
	v_fma_f32 v13, -v8, v11, v1
	v_fmac_f32_e32 v11, v13, v10
	v_fma_f32 v1, -v8, v11, v1
	v_div_fmas_f32 v1, v1, v10, v11
	v_div_fixup_f32 v8, v1, v12, v14
	v_pk_mul_f32 v[6:7], v[8:9], v[6:7]
	s_nop 0
	v_cvt_pk_bf16_f32 v5, v6, v7
	global_store_dwordx2 v[2:3], v[4:5], off offset:240

;   DI float* park() const { return (float*)ws; }
; #define ATTN_LOAD(KT) { ATTN_LOAD_K(KT); ATTN_LOAD_V(KT); }
; #define ATTN_STORE(ST) { ATTN_STORE_K(ST); ATTN_STORE_V(ST); }
; template <int DQK, int NMAP, int DV> ...
;     ...
;   ATTN_LOAD(kt_lo);
;   ATTN_STORE(0);
;   if (kt_lo < kt_hi) ATTN_LOAD(kt_lo + 1);
; DI void diff_item(const Params& p, int b, int hh, int qt, float lam, char* smem) {
;     ...
;   f32x4* park = (f32x4*)(p.park() + ((size_t)blockIdx.x * NTH + tid_) * 64);
;   attn_core<64, 1, 128>(zb + 2304 + hh * 128, LDZ1, zb + 3328 + hh * 128, LDZ1, 64, nullptr, 0, vt, qt * 256, 0, qt * 4 + 3, 0.125f * LOG2E, -1e30f, 0.f, 0, smem, O, ls);
;   {
;     const float i0 = 1.f / ls[0];
; #pragma unroll
;     for (int db = 0; db < 4; ++db)
; #pragma unroll
;       for (int j = 0; j < 4; ++j) { f32x4 v = {O[0][db][4 * j] * i0, O[0][db][4 * j + 1] * i0, O[0][db][4 * j + 2] * i0, O[0][db][4 * j + 3] * i0}; park[db * 4 + j] = v; }
;   }
.LBB0_1513:
	v_and_b32_e32 v2, 64, v198
	v_xor_b32_e32 v1, 32, v198
	v_add_u32_e32 v2, 64, v2
	v_cmp_lt_i32_e32 vcc, v1, v2
	v_ashrrev_i32_e32 v141, 31, v140
	v_and_b32_e32 v2, 63, v140
	v_lshlrev_b32_e32 v2, 4, v2
	v_and_b32_e32 v3, 0xffffffc0, v140
	v_lshl_add_u32 v2, v3, 8, v2
	v_add_u32_e32 v2, 0x1000, v2
	v_mov_b32_e32 v3, 0
	v_cndmask_b32_e32 v1, v198, v1, vcc
	v_lshlrev_b32_e32 v155, 2, v1
	ds_bpermute_b32 v1, v155, v156
	v_lshl_add_u64 v[142:143], s[8:9], 0, v[2:3]
	s_waitcnt lgkmcnt(0)
	s_barrier
	v_add_f32_e32 v1, v156, v1
	v_div_scale_f32 v2, s[18:19], v1, v1, 1.0
	v_rcp_f32_e32 v3, v2
	v_mov_b64_e32 v[14:15], s[16:17]
	s_mov_b32 s19, 0
	v_mov_b32_e32 v141, 0xf149f2ca
	v_fma_f32 v4, -v2, v3, 1.0
	v_fmac_f32_e32 v3, v4, v3
	v_div_scale_f32 v4, vcc, 1.0, v1, 1.0
	v_mul_f32_e32 v5, v4, v3
	v_fma_f32 v6, -v2, v5, v4
	v_fmac_f32_e32 v5, v6, v3
	v_fma_f32 v2, -v2, v5, v4
	v_div_fmas_f32 v2, v2, v3, v5
	v_div_fixup_f32 v6, v2, v1, 1.0
	v_pk_mul_f32 v[2:3], v[64:65], v[6:7] op_sel_hi:[1,0]
	v_pk_mul_f32 v[4:5], v[66:67], v[6:7] op_sel_hi:[1,0]
	global_store_dwordx4 v[142:143], v[2:5], off offset:-4096
	v_mov_b32_e32 v1, v206
	v_mov_b32_e32 v158, 0
	v_pk_mul_f32 v[2:3], v[68:69], v[6:7] op_sel_hi:[1,0]
	v_pk_mul_f32 v[4:5], v[70:71], v[6:7] op_sel_hi:[1,0]
	global_store_dwordx4 v[142:143], v[2:5], off offset:-3072
	s_mov_b32 s24, 0
	s_nop 0
	v_pk_mul_f32 v[2:3], v[72:73], v[6:7] op_sel_hi:[1,0]
	v_pk_mul_f32 v[4:5], v[74:75], v[6:7] op_sel_hi:[1,0]
	global_store_dwordx4 v[142:143], v[2:5], off offset:-2048
	s_nop 1
	v_pk_mul_f32 v[2:3], v[76:77], v[6:7] op_sel_hi:[1,0]
	v_pk_mul_f32 v[4:5], v[78:79], v[6:7] op_sel_hi:[1,0]
	global_store_dwordx4 v[142:143], v[2:5], off offset:-1024
	s_nop 1
	v_pk_mul_f32 v[2:3], v[48:49], v[6:7] op_sel_hi:[1,0]
	v_pk_mul_f32 v[4:5], v[50:51], v[6:7] op_sel_hi:[1,0]
	global_store_dwordx4 v[142:143], v[2:5], off
	s_nop 1
	v_pk_mul_f32 v[2:3], v[52:53], v[6:7] op_sel_hi:[1,0]
	v_pk_mul_f32 v[4:5], v[54:55], v[6:7] op_sel_hi:[1,0]
	global_store_dwordx4 v[142:143], v[2:5], off offset:1024
	s_nop 1
	v_pk_mul_f32 v[2:3], v[56:57], v[6:7] op_sel_hi:[1,0]
	v_pk_mul_f32 v[4:5], v[58:59], v[6:7] op_sel_hi:[1,0]
	global_store_dwordx4 v[142:143], v[2:5], off offset:2048
	s_nop 1
	v_pk_mul_f32 v[2:3], v[60:61], v[6:7] op_sel_hi:[1,0]
	v_pk_mul_f32 v[4:5], v[62:63], v[6:7] op_sel_hi:[1,0]
	global_store_dwordx4 v[142:143], v[2:5], off offset:3072
	s_nop 1
	v_pk_mul_f32 v[2:3], v[32:33], v[6:7] op_sel_hi:[1,0]
	v_pk_mul_f32 v[4:5], v[34:35], v[6:7] op_sel_hi:[1,0]
	s_mov_b32 s98, 0x2000
	s_mov_b32 s99, 0
	v_lshl_add_u64 v[142:143], v[142:143], 0, s[98:99]
	global_store_dwordx4 v[142:143], v[2:5], off offset:-4096
	s_nop 1
	v_pk_mul_f32 v[2:3], v[36:37], v[6:7] op_sel_hi:[1,0]
	v_pk_mul_f32 v[4:5], v[38:39], v[6:7] op_sel_hi:[1,0]
	global_store_dwordx4 v[142:143], v[2:5], off offset:-3072
	s_nop 1
	v_pk_mul_f32 v[2:3], v[40:41], v[6:7] op_sel_hi:[1,0]
	v_pk_mul_f32 v[4:5], v[42:43], v[6:7] op_sel_hi:[1,0]
	global_store_dwordx4 v[142:143], v[2:5], off offset:-2048
	s_nop 1
	v_pk_mul_f32 v[2:3], v[44:45], v[6:7] op_sel_hi:[1,0]
	v_pk_mul_f32 v[4:5], v[46:47], v[6:7] op_sel_hi:[1,0]
	global_store_dwordx4 v[142:143], v[2:5], off offset:-1024
	s_nop 1
	v_pk_mul_f32 v[2:3], v[16:17], v[6:7] op_sel_hi:[1,0]
	v_pk_mul_f32 v[4:5], v[18:19], v[6:7] op_sel_hi:[1,0]
	global_store_dwordx4 v[142:143], v[2:5], off
	v_mov_b32_e32 v19, v0
	s_nop 0
	v_pk_mul_f32 v[2:3], v[20:21], v[6:7] op_sel_hi:[1,0]
	v_pk_mul_f32 v[4:5], v[22:23], v[6:7] op_sel_hi:[1,0]
	global_store_dwordx4 v[142:143], v[2:5], off offset:1024
	s_nop 1
	v_pk_mul_f32 v[2:3], v[24:25], v[6:7] op_sel_hi:[1,0]
	v_pk_mul_f32 v[4:5], v[26:27], v[6:7] op_sel_hi:[1,0]
	global_store_dwordx4 v[142:143], v[2:5], off offset:2048
	v_mov_b64_e32 v[24:25], s[2:3]
	v_mov_b32_e32 v27, v0
	v_pk_mul_f32 v[2:3], v[28:29], v[6:7] op_sel_hi:[1,0]
	v_pk_mul_f32 v[4:5], v[30:31], v[6:7] op_sel_hi:[1,0]
	global_store_dwordx4 v[142:143], v[2:5], off offset:3072
	s_nop 0
	v_ashrrev_i32_e32 v20, 3, v1
	v_ashrrev_i32_e32 v2, 31, v1
	v_lshrrev_b32_e32 v2, 29, v2
	v_add_u32_e32 v4, v1, v2
	v_ashrrev_i32_e32 v28, 3, v4
	v_and_b32_e32 v4, -8, v4
	v_sub_u32_e32 v29, v1, v4
	v_lshlrev_b32_e32 v4, 3, v29
	v_ashrrev_i32_e32 v5, 31, v4
	v_lshlrev_b64 v[16:17], 1, v[4:5]
	v_lshlrev_b32_e32 v4, 3, v1
	v_mad_i64_i32 v[2:3], s[16:17], v28, s39, v[14:15]
	v_and_b32_e32 v162, 56, v4
	v_add_u32_e32 v10, 0x200, v1
	v_lshlrev_b32_e32 v18, 1, v162
	v_ashrrev_i32_e32 v21, 31, v20
	v_ashrrev_i32_e32 v22, 3, v10
	v_readfirstlane_b32 s16, v1
	v_lshl_add_u64 v[144:145], s[0:1], 0, v[18:19]
	v_lshlrev_b64 v[146:147], 13, v[20:21]
	v_ashrrev_i32_e32 v23, 31, v22
	s_ashr_i32 s16, s16, 1
	v_lshl_add_u64 v[2:3], v[2:3], 0, v[16:17]
	v_lshl_add_u64 v[6:7], v[144:145], 0, v[146:147]
	v_lshlrev_b64 v[148:149], 13, v[22:23]
	s_andn2_b32 s16, s16, 31
	global_load_dwordx4 v[2:5], v[2:3], off offset:128
	s_nop 0
	global_load_dwordx4 v[6:9], v[6:7], off
	v_lshl_add_u64 v[10:11], v[144:145], 0, v[148:149]
	v_and_b32_e32 v159, 31, v1
	s_add_i32 s18, s16, s52
	global_load_dwordx4 v[10:13], v[10:11], off
	v_bfe_u32 v1, v1, 5, 1
	v_or_b32_e32 v156, s18, v159
	v_add_u32_e32 v21, 64, v28
	v_mad_i64_i32 v[24:25], s[2:3], v156, s39, v[24:25]
	v_lshlrev_b32_e32 v26, 4, v1
	v_mad_i64_i32 v[14:15], s[2:3], v21, s39, v[14:15]
	v_lshl_add_u64 v[24:25], v[24:25], 0, v[26:27]
	v_lshl_add_u64 v[14:15], v[14:15], 0, v[16:17]
	global_load_dwordx4 v[124:127], v[24:25], off offset:128
	global_load_dwordx4 v[120:123], v[24:25], off offset:160
	global_load_dwordx4 v[116:119], v[24:25], off offset:192
	global_load_dwordx4 v[112:115], v[24:25], off offset:224
	global_load_dwordx4 v[136:139], v[14:15], off offset:128
	v_lshl_add_u64 v[14:15], s[0:1], 0, v[146:147]
	v_lshl_add_u64 v[14:15], v[14:15], 0, v[18:19]
	v_lshl_add_u64 v[24:25], s[0:1], 0, v[148:149]
	v_lshl_add_u64 v[24:25], v[24:25], 0, v[18:19]
	global_load_dwordx4 v[132:135], v[14:15], off offset:128
	global_load_dwordx4 v[128:131], v[24:25], off offset:128
	v_mul_lo_u32 v14, v28, s40
	v_lshlrev_b32_e32 v15, 4, v29
	v_add3_u32 v166, 16, v14, v15
	v_add_u32_e32 v167, 16, v18
	v_mul_lo_u32 v163, v20, s41
	s_or_b32 s17, s18, 31
	s_add_i32 s0, s16, 0xf00
	v_lshlrev_b32_e32 v160, 3, v1
	v_mul_lo_u32 v164, v22, s41
	v_lshlrev_b32_e32 v157, 2, v1
	v_or_b32_e32 v1, s0, v159
	s_add_u32 s0, s57, s56
	s_addc_u32 s1, 0, 0
	v_sub_u32_e32 v1, v1, v157
	v_mov_b32_e32 v14, v0
	v_mov_b32_e32 v15, v0
	v_subrev_u32_e32 v168, s62, v1
	v_mov_b32_e32 v1, v0
	v_mul_u32_u24_e32 v161, 0x90, v159
	v_mul_u32_u24_e32 v165, 0x88, v159
	s_waitcnt vmcnt(9)
; #define ATTN_LOAD(KT) { ATTN_LOAD_K(KT); ATTN_LOAD_V(KT); }
; #define ATTN_STORE(ST) { ATTN_STORE_K(ST); ATTN_STORE_V(ST); }
; template <int DQK, int NMAP, int DV> ...
;     ...
;   float m[NMAP];
; #pragma unroll
;   for (int c = 0; c < NMAP; ++c) {
;     m[c] = m_init; lsum[c] = g == 0 ? l_init : 0.f;
; #pragma unroll
;     for (int db = 0; db < NDB; ++db)
; #pragma unroll
;       for (int r = 0; r < 16; ++r) O[c][db][r] = 0.f;
;   }
;   u32x4 rk[NKC], rv[NVC];
;     ...
;   ATTN_LOAD(kt_lo);
;   ATTN_STORE(0);
;   if (kt_lo < kt_hi) ATTN_LOAD(kt_lo + 1);
;   const int qmin = q0 + 32 * w, qmax = qmin + 31, qpos = qmin + l32;
	ds_write_b128 v166, v[2:5]
	v_add3_u32 v2, v167, v163, s42
	s_waitcnt vmcnt(8)
	ds_write2_b64 v2, v[6:7], v[8:9] offset1:1
	v_add3_u32 v2, v167, v164, s42
	v_mov_b32_e32 v4, v0
	s_waitcnt vmcnt(7)
	ds_write2_b64 v2, v[10:11], v[12:13] offset1:1
	v_mov_b64_e32 v[2:3], s[0:1]
	v_mad_i64_i32 v[2:3], s[0:1], v28, s39, v[2:3]
	v_lshl_add_u64 v[2:3], v[2:3], 0, v[16:17]
	v_lshl_add_u64 v[150:151], s[12:13], 0, v[2:3]
	v_mov_b32_e32 v2, v0
	v_mov_b32_e32 v3, v0
	v_mov_b32_e32 v5, v0
	v_mov_b32_e32 v6, v0
	v_mov_b32_e32 v7, v0
	v_mov_b32_e32 v8, v0
	v_mov_b32_e32 v9, v0
	v_mov_b32_e32 v10, v0
	v_mov_b32_e32 v11, v0
	v_mov_b32_e32 v12, v0
	v_mov_b32_e32 v13, v0
	v_mov_b64_e32 v[30:31], v[14:15]
	v_mov_b64_e32 v[46:47], v[14:15]
	v_mov_b64_e32 v[62:63], v[14:15]
	v_mov_b64_e32 v[78:79], v[14:15]
	v_mov_b64_e32 v[28:29], v[12:13]
	v_mov_b64_e32 v[26:27], v[10:11]
	v_mov_b64_e32 v[24:25], v[8:9]
	v_mov_b64_e32 v[22:23], v[6:7]
	v_mov_b64_e32 v[20:21], v[4:5]
	v_mov_b64_e32 v[18:19], v[2:3]
	v_mov_b64_e32 v[16:17], v[0:1]
	v_mov_b64_e32 v[44:45], v[12:13]
	v_mov_b64_e32 v[42:43], v[10:11]
	v_mov_b64_e32 v[40:41], v[8:9]
	v_mov_b64_e32 v[38:39], v[6:7]
	v_mov_b64_e32 v[36:37], v[4:5]
	v_mov_b64_e32 v[34:35], v[2:3]
	v_mov_b64_e32 v[32:33], v[0:1]
	v_mov_b64_e32 v[60:61], v[12:13]
	v_mov_b64_e32 v[58:59], v[10:11]
	v_mov_b64_e32 v[56:57], v[8:9]
	v_mov_b64_e32 v[54:55], v[6:7]
	v_mov_b64_e32 v[52:53], v[4:5]
	v_mov_b64_e32 v[50:51], v[2:3]
	v_mov_b64_e32 v[48:49], v[0:1]
	v_mov_b64_e32 v[76:77], v[12:13]
	v_mov_b64_e32 v[74:75], v[10:11]
	v_mov_b64_e32 v[72:73], v[8:9]
	v_mov_b64_e32 v[70:71], v[6:7]
	v_mov_b64_e32 v[68:69], v[4:5]
	v_mov_b64_e32 v[66:67], v[2:3]
	v_mov_b64_e32 v[64:65], v[0:1]
	s_branch .LBB0_1516
